# stick-breaking: separate quarter body without causal masking for quarters fully below the wave's rows (16 compares and 28 selects fewer)
# speedup vs baseline: 1.0033x; 1.0033x over previous
; #define LAS __attribute__((address_space(3)))
; #define S_LOAD(key0) do { st0 = *(const u32x4*)(kg + (size_t)(key0) * 1024); st1 = *(const u32x4*)(kg + (size_t)((key0) + 64) * 1024); st2 = *(const u32x4*)(vg + (size_t)(key0) * 1024); st3 = *(const u32x4*)(vg + (size_t)((key0) + 64) * 1024); } while (0)
; __device__ __forceinline__ void sb_unit(const Frame& F, int b, int hd, int qi, int dry) {
;     ...
;     for (int it = 0; it < nt; ++it) {
;         const bool meta = (it > jmax);
;         const int key0 = meta ? 0 : NMETA + 128 * (jmax - it);
;         if (it + 1 < nt) { const int nk = (it + 1 > jmax) ? 0 : NMETA + 128 * (jmax - it - 1); S_LOAD(nk); }
;         if (!dead && (meta || key0 < tqw + 31)) {
;             const LAS unsigned char* kb = lds + kra + (it & 1) * SK_BUF;
;             const LAS unsigned char* vb = lds + vra + (it & 1) * SV_BUF;
.LBB0_337:
	s_xor_b64 s[0:1], s[0:1], -1
	s_andn2_b64 vcc, exec, s[0:1]
	s_mov_b64 s[0:1], -1
	s_cbranch_vccnz .LBB0_350
	s_add_i32 s35, s33, 0xffffff10
	s_cmp_gt_u32 s36, s29
	s_cselect_b64 s[18:19], -1, 0
	s_and_b64 s[0:1], s[18:19], exec
	s_cselect_b32 s35, 0, s35
	s_cmp_lt_i32 s35, s30
	s_cselect_b64 s[0:1], -1, 0
	s_or_b64 s[0:1], s[18:19], s[0:1]
	s_andn2_b64 vcc, exec, s[0:1]
	s_mov_b64 s[0:1], 0
	s_cbranch_vccnz .LBB0_350
	s_and_b32 s0, s36, 1
	s_mul_i32 s36, s0, 0x4800
	s_mul_i32 s37, s0, 0x6000
	s_or_b32 s0, s35, 0x41
	s_cmp_ge_i32 s0, s26
	s_cselect_b64 s[0:1], -1, 0
	s_or_b64 s[0:1], s[18:19], s[0:1]
	s_and_b64 vcc, exec, s[0:1]
	v_add_u32_e32 v129, s36, v118
	v_or_b32_e32 v127, s35, v205
	v_add_u32_e32 v128, s37, v119
	s_cbranch_vccnz .LBB0_341
	s_add_i32 s61, s35, 128
	s_cmp_le_i32 s61, s26
	s_cbranch_scc1 .Lsbq_nomask_6
	ds_read_b128 v[32:35], v129 offset:13824
	ds_read_b128 v[214:217], v129 offset:13856
	ds_read_b128 v[210:213], v129 offset:13888
	ds_read_b128 v[130:133], v129 offset:13920
	ds_read_b64_tr_b16 v[92:93], v128 offset:55296
	ds_read_b64_tr_b16 v[94:95], v128 offset:56832
	ds_read_b64_tr_b16 v[90:91], v128 offset:56896
	ds_read_b64_tr_b16 v[88:89], v128 offset:55360
	ds_read_b64_tr_b16 v[84:85], v128 offset:58368
	ds_read_b64_tr_b16 v[86:87], v128 offset:59904
	ds_read_b64_tr_b16 v[82:83], v128 offset:59968
	ds_read_b64_tr_b16 v[80:81], v128 offset:58432
	v_exp_f32_e32 v135, v125
	v_sub_u32_e32 v134, v115, v127
	v_cmp_lt_i32_e32 vcc, 0, v134
	s_waitcnt lgkmcnt(11)
	v_mfma_f32_32x32x16_bf16 v[32:47], v[32:35], v[48:51], 0
	v_cmp_lt_i32_e64 s[0:1], 27, v134
	s_waitcnt lgkmcnt(10)
	v_mfma_f32_32x32x16_bf16 v[32:47], v[214:217], v[52:55], v[32:47]
	s_waitcnt lgkmcnt(9)
	v_mfma_f32_32x32x16_bf16 v[32:47], v[210:213], v[56:59], v[32:47]
	s_waitcnt lgkmcnt(8)
	v_mfma_f32_32x32x16_bf16 v[32:47], v[130:133], v[60:63], v[32:47]
	s_nop 11
	v_min_f32_e64 v32, -v32, s60
	v_min_f32_e64 v33, -v33, s60
	v_exp_f32_e32 v32, v32
	v_min_f32_e64 v34, -v34, s60
	v_exp_f32_e32 v33, v33
	v_exp_f32_e32 v34, v34
	v_min_f32_e64 v35, -v35, s60
	v_exp_f32_e32 v130, v35
	v_add_f32_e32 v35, 1.0, v32
	v_add_f32_e32 v131, 1.0, v33
	v_rcp_f32_e32 v35, v35
	v_add_f32_e32 v132, 1.0, v34
	v_rcp_f32_e32 v131, v131
	v_min_f32_e64 v36, -v36, s60
	v_rcp_f32_e32 v132, v132
	v_exp_f32_e32 v36, v36
	v_add_f32_e32 v133, 1.0, v130
	v_rcp_f32_e32 v136, v133
	v_mul_f32_e32 v32, v32, v35
	v_mul_f32_e32 v133, v135, v35
	v_mul_f32_e32 v33, v33, v131
	v_mul_f32_e32 v137, v135, v131
	v_cndmask_b32_e32 v35, 1.0, v32, vcc
	v_cndmask_b32_e32 v138, 0, v133, vcc
	v_cmp_lt_i32_e32 vcc, 1, v134
	v_mul_f32_e32 v34, v34, v132
	v_mul_f32_e32 v32, v135, v132
	v_cndmask_b32_e32 v131, 1.0, v33, vcc
	v_cndmask_b32_e32 v137, 0, v137, vcc
	v_cmp_lt_i32_e32 vcc, 2, v134
	v_min_f32_e64 v39, -v39, s60
	v_cndmask_b32_e32 v33, 1.0, v34, vcc
	v_add_f32_e32 v34, 1.0, v36
	v_rcp_f32_e32 v34, v34
	v_cndmask_b32_e32 v139, 0, v32, vcc
	v_mul_f32_e32 v32, v130, v136
	v_cmp_lt_i32_e32 vcc, 3, v134
	v_exp_f32_e32 v39, v39
	v_cndmask_b32_e32 v133, 1.0, v32, vcc
	v_mul_f32_e32 v32, v135, v136
	v_cndmask_b32_e32 v136, 0, v32, vcc
	v_mul_f32_e32 v32, v36, v34
	v_min_f32_e64 v36, -v37, s60
	v_exp_f32_e32 v36, v36
	v_cmp_lt_i32_e32 vcc, 8, v134
	v_mul_f32_e32 v34, v135, v34
	v_cndmask_b32_e32 v140, 0, v34, vcc
	v_add_f32_e32 v34, 1.0, v36
	v_rcp_f32_e32 v34, v34
	v_min_f32_e64 v37, -v38, s60
	v_exp_f32_e32 v37, v37
	v_cndmask_b32_e32 v32, 1.0, v32, vcc
	v_mul_f32_e32 v36, v36, v34
	v_cmp_lt_i32_e32 vcc, 9, v134
	v_mul_f32_e32 v34, v135, v34
	v_min_f32_e64 v42, -v42, s60
	v_cndmask_b32_e32 v38, 1.0, v36, vcc
	v_add_f32_e32 v36, 1.0, v37
	v_rcp_f32_e32 v36, v36
	v_cndmask_b32_e32 v141, 0, v34, vcc
	v_cmp_lt_i32_e32 vcc, 10, v134
	v_exp_f32_e32 v42, v42
	v_mul_f32_e32 v34, v37, v36
	v_add_f32_e32 v37, 1.0, v39
	v_rcp_f32_e32 v37, v37
	v_cndmask_b32_e32 v142, 1.0, v34, vcc
	v_mul_f32_e32 v34, v135, v36
	v_cndmask_b32_e32 v143, 0, v34, vcc
	v_mul_f32_e32 v34, v39, v37
	v_cmp_lt_i32_e32 vcc, 11, v134
	v_min_f32_e64 v36, -v40, s60
	v_exp_f32_e32 v36, v36
	v_cndmask_b32_e32 v39, 1.0, v34, vcc
	v_mul_f32_e32 v34, v135, v37
	v_min_f32_e64 v37, -v41, s60
	v_exp_f32_e32 v37, v37
	v_cndmask_b32_e32 v40, 0, v34, vcc
	v_add_f32_e32 v34, 1.0, v36
	v_rcp_f32_e32 v34, v34
	v_add_f32_e32 v41, 1.0, v37
	v_rcp_f32_e32 v41, v41
	v_cmp_lt_i32_e32 vcc, 16, v134
	v_mul_f32_e32 v36, v36, v34
	v_mul_f32_e32 v34, v135, v34
	v_cndmask_b32_e32 v144, 0, v34, vcc
	v_mul_f32_e32 v34, v37, v41
	v_add_f32_e32 v37, 1.0, v42
	v_rcp_f32_e32 v37, v37
	v_cndmask_b32_e32 v36, 1.0, v36, vcc
	v_cmp_lt_i32_e32 vcc, 17, v134
	v_min_f32_e64 v45, -v45, s60
	v_cndmask_b32_e32 v145, 1.0, v34, vcc
	v_mul_f32_e32 v34, v135, v41
	v_cndmask_b32_e32 v41, 0, v34, vcc
	v_mul_f32_e32 v34, v42, v37
	v_cmp_lt_i32_e32 vcc, 18, v134
	v_min_f32_e64 v42, -v43, s60
	v_exp_f32_e32 v42, v42
	v_cndmask_b32_e32 v43, 1.0, v34, vcc
	v_mul_f32_e32 v34, v135, v37
	v_min_f32_e64 v37, -v44, s60
	v_exp_f32_e32 v37, v37
	v_cndmask_b32_e32 v146, 0, v34, vcc
	v_add_f32_e32 v34, 1.0, v42
	v_rcp_f32_e32 v34, v34
	v_add_f32_e32 v44, 1.0, v37
	v_rcp_f32_e32 v44, v44
	v_exp_f32_e32 v45, v45
	v_min_f32_e64 v46, -v46, s60
	v_min_f32_e64 v47, -v47, s60
	v_exp_f32_e32 v46, v46
	v_exp_f32_e32 v47, v47
	v_mul_f32_e32 v42, v42, v34
	v_cmp_lt_i32_e32 vcc, 19, v134
	v_mul_f32_e32 v34, v135, v34
	v_add_f32_e32 v130, 1.0, v46
	v_cndmask_b32_e32 v147, 0, v34, vcc
	v_mul_f32_e32 v34, v37, v44
	v_add_f32_e32 v37, 1.0, v45
	v_rcp_f32_e32 v37, v37
	v_add_f32_e32 v132, 1.0, v47
	v_rcp_f32_e32 v130, v130
	v_rcp_f32_e32 v132, v132
	v_cndmask_b32_e32 v42, 1.0, v42, vcc
	v_cmp_lt_i32_e32 vcc, 24, v134
	v_mul_f32_e32 v44, v135, v44
	v_mul_f32_e32 v45, v45, v37
	v_cndmask_b32_e32 v34, 1.0, v34, vcc
	v_cndmask_b32_e32 v44, 0, v44, vcc
	v_cmp_lt_i32_e32 vcc, 25, v134
	v_mul_f32_e32 v37, v135, v37
	v_mul_f32_e32 v46, v46, v130
	v_cndmask_b32_e32 v45, 1.0, v45, vcc
	v_cndmask_b32_e32 v37, 0, v37, vcc
	v_cmp_lt_i32_e32 vcc, 26, v134
	v_mul_f32_e32 v47, v47, v132
	v_cndmask_b32_e64 v47, 1.0, v47, s[0:1]
	v_cndmask_b32_e32 v46, 1.0, v46, vcc
	v_mul_f32_e32 v34, v34, v45
	v_mul_f32_e32 v134, v46, v47
	v_mul_f32_e32 v134, v34, v134
	v_mov_b32_e32 v148, v134
	v_mov_b32_e32 v240, v134
	s_nop 1
	v_permlane32_swap_b32_e32 v148, v240
	v_cndmask_b32_e64 v148, v148, v240, s[2:3]
	v_mul_f32_e32 v34, v135, v130
	v_cndmask_b32_e32 v149, 0, v34, vcc
	v_mul_f32_e32 v34, v135, v132
	v_cndmask_b32_e64 v34, 0, v34, s[0:1]
	s_waitcnt lgkmcnt(0)
	v_cndmask_b32_e64 v130, 1.0, v148, s[2:3]
	v_mul_f32_e32 v135, v34, v130
	v_mul_f32_e32 v34, v36, v145
	v_mul_f32_e32 v36, v43, v42
	v_mul_f32_e32 v36, v34, v36
	v_mul_f32_e32 v32, v32, v38
	v_mul_f32_e32 v34, v142, v39
	v_mov_b32_e32 v150, v36
	v_mov_b32_e32 v240, v36
	s_nop 1
	v_permlane32_swap_b32_e32 v150, v240
	v_cndmask_b32_e64 v150, v150, v240, s[2:3]
	v_mul_f32_e32 v34, v32, v34
	v_mul_f32_e32 v47, v47, v130
	v_mov_b32_e32 v130, v34
	v_mov_b32_e32 v240, v34
	s_nop 1
	v_permlane32_swap_b32_e32 v130, v240
	v_cndmask_b32_e64 v130, v130, v240, s[2:3]
	v_mul_f32_e32 v46, v46, v47
	v_mul_f32_e32 v32, v134, v148
	s_waitcnt lgkmcnt(1)
	v_mul_f32_e32 v132, v36, v150
	v_mul_f32_e32 v45, v45, v46
	v_mul_f32_e32 v46, v37, v46
	s_waitcnt lgkmcnt(0)
	v_cndmask_b32_e64 v134, 1.0, v130, s[2:3]
	v_pk_mul_f32 v[36:37], v[32:33], v[132:133]
	v_pk_mul_f32 v[34:35], v[34:35], v[130:131]
	v_mul_f32_e32 v132, v36, v134
	v_mul_f32_e32 v134, v39, v132
	v_mul_f32_e32 v142, v142, v134
	v_mul_f32_e32 v148, v38, v142
	v_pk_mul_f32 v[38:39], v[34:35], v[36:37]
	v_mov_b32_e32 v130, v39
	v_mov_b32_e32 v240, v39
	s_nop 1
	v_permlane32_swap_b32_e32 v130, v240
	v_cndmask_b32_e64 v130, v130, v240, s[2:3]
	v_mul_f32_e32 v37, v40, v132
	v_mul_f32_e32 v40, v143, v134
	v_mul_f32_e32 v36, v141, v142
	v_mul_f32_e32 v132, v140, v148
	s_waitcnt lgkmcnt(0)
	v_cndmask_b32_e64 v34, 1.0, v130, s[2:3]
	v_mul_f32_e32 v34, v38, v34
	v_mul_f32_e32 v35, v133, v34
	v_mul_f32_e32 v33, v33, v35
	v_mul_f32_e32 v131, v131, v33
	v_mul_f32_e32 v133, v136, v34
	v_mul_f32_e32 v35, v139, v35
	v_mul_f32_e32 v33, v137, v33
	v_mul_f32_e32 v34, v138, v131
	v_cvt_pk_bf16_f32 v34, v34, v33
	v_cvt_pk_bf16_f32 v35, v35, v133
	v_cvt_pk_bf16_f32 v36, v132, v36
	v_cvt_pk_bf16_f32 v37, v40, v37
	v_cndmask_b32_e64 v33, 1.0, v150, s[2:3]
	v_mul_f32_e32 v32, v32, v33
	v_mfma_f32_32x32x16_bf16 v[16:31], v[92:95], v[34:37], v[16:31]
	v_mul_f32_e32 v33, v42, v32
	v_mul_f32_e32 v42, v43, v33
	v_mul_f32_e32 v43, v145, v42
	v_mul_f32_e32 v47, v149, v47
	v_mul_f32_e32 v40, v44, v45
	v_mul_f32_e32 v44, v147, v32
	v_mul_f32_e32 v33, v146, v33
	v_mfma_f32_32x32x16_bf16 v[0:15], v[88:91], v[34:37], v[0:15]
	v_mul_f32_e32 v32, v41, v42
	v_mul_f32_e32 v34, v144, v43
	v_cvt_pk_bf16_f32 v32, v34, v32
	v_cvt_pk_bf16_f32 v33, v33, v44
	v_cvt_pk_bf16_f32 v34, v40, v46
	v_cvt_pk_bf16_f32 v35, v47, v135
	v_mul_f32_e32 v36, v39, v130
	v_mul_f32_e32 v36, v38, v36
	v_mfma_f32_32x32x16_bf16 v[16:31], v[84:87], v[32:35], v[16:31]
	v_log_f32_e32 v36, v36
	s_nop 0
	v_add_f32_e32 v125, v125, v36
	v_mfma_f32_32x32x16_bf16 v[0:15], v[80:83], v[32:35], v[0:15]
	s_branch .LBB0_341
.Lsbq_nomask_6:
	ds_read_b128 v[32:35], v129 offset:13824
	ds_read_b128 v[214:217], v129 offset:13856
	ds_read_b128 v[210:213], v129 offset:13888
	ds_read_b128 v[130:133], v129 offset:13920
	ds_read_b64_tr_b16 v[92:93], v128 offset:55296
	ds_read_b64_tr_b16 v[94:95], v128 offset:56832
	ds_read_b64_tr_b16 v[90:91], v128 offset:56896
	ds_read_b64_tr_b16 v[88:89], v128 offset:55360
	ds_read_b64_tr_b16 v[84:85], v128 offset:58368
	ds_read_b64_tr_b16 v[86:87], v128 offset:59904
	ds_read_b64_tr_b16 v[82:83], v128 offset:59968
	ds_read_b64_tr_b16 v[80:81], v128 offset:58432
	v_exp_f32_e32 v135, v125
	s_waitcnt lgkmcnt(11)
	v_mfma_f32_32x32x16_bf16 v[32:47], v[32:35], v[48:51], 0
	s_waitcnt lgkmcnt(10)
	v_mfma_f32_32x32x16_bf16 v[32:47], v[214:217], v[52:55], v[32:47]
	s_waitcnt lgkmcnt(9)
	v_mfma_f32_32x32x16_bf16 v[32:47], v[210:213], v[56:59], v[32:47]
	s_waitcnt lgkmcnt(8)
	v_mfma_f32_32x32x16_bf16 v[32:47], v[130:133], v[60:63], v[32:47]
	s_nop 11
	v_min_f32_e64 v32, -v32, s60
	v_min_f32_e64 v33, -v33, s60
	v_exp_f32_e32 v32, v32
	v_min_f32_e64 v34, -v34, s60
	v_exp_f32_e32 v33, v33
	v_exp_f32_e32 v34, v34
	v_min_f32_e64 v35, -v35, s60
	v_exp_f32_e32 v130, v35
	v_add_f32_e32 v35, 1.0, v32
	v_add_f32_e32 v131, 1.0, v33
	v_rcp_f32_e32 v35, v35
	v_add_f32_e32 v132, 1.0, v34
	v_rcp_f32_e32 v131, v131
	v_min_f32_e64 v36, -v36, s60
	v_rcp_f32_e32 v132, v132
	v_exp_f32_e32 v36, v36
	v_add_f32_e32 v133, 1.0, v130
	v_rcp_f32_e32 v136, v133
	v_mul_f32_e32 v32, v32, v35
	v_mul_f32_e32 v138, v135, v35
	v_mul_f32_e32 v33, v33, v131
	v_mul_f32_e32 v137, v135, v131
	v_mov_b32_e32 v35, v32
	v_mul_f32_e32 v34, v34, v132
	v_mul_f32_e32 v139, v135, v132
	v_mov_b32_e32 v131, v33
	v_min_f32_e64 v39, -v39, s60
	v_mov_b32_e32 v33, v34
	v_add_f32_e32 v34, 1.0, v36
	v_rcp_f32_e32 v34, v34
	v_mul_f32_e32 v133, v130, v136
	v_exp_f32_e32 v39, v39
	v_mul_f32_e32 v136, v135, v136
	v_mul_f32_e32 v32, v36, v34
	v_min_f32_e64 v36, -v37, s60
	v_exp_f32_e32 v36, v36
	v_mul_f32_e32 v140, v135, v34
	v_add_f32_e32 v34, 1.0, v36
	v_rcp_f32_e32 v34, v34
	v_min_f32_e64 v37, -v38, s60
	v_exp_f32_e32 v37, v37
	v_mul_f32_e32 v38, v36, v34
	v_mul_f32_e32 v141, v135, v34
	v_min_f32_e64 v42, -v42, s60
	v_add_f32_e32 v36, 1.0, v37
	v_rcp_f32_e32 v36, v36
	v_exp_f32_e32 v42, v42
	v_mul_f32_e32 v142, v37, v36
	v_add_f32_e32 v37, 1.0, v39
	v_rcp_f32_e32 v37, v37
	v_mul_f32_e32 v143, v135, v36
	v_mul_f32_e32 v39, v39, v37
	v_min_f32_e64 v36, -v40, s60
	v_exp_f32_e32 v36, v36
	v_mul_f32_e32 v40, v135, v37
	v_min_f32_e64 v37, -v41, s60
	v_exp_f32_e32 v37, v37
	v_add_f32_e32 v34, 1.0, v36
	v_rcp_f32_e32 v34, v34
	v_add_f32_e32 v41, 1.0, v37
	v_rcp_f32_e32 v41, v41
	v_mul_f32_e32 v36, v36, v34
	v_mul_f32_e32 v144, v135, v34
	v_mul_f32_e32 v145, v37, v41
	v_add_f32_e32 v37, 1.0, v42
	v_rcp_f32_e32 v37, v37
	v_min_f32_e64 v45, -v45, s60
	v_mul_f32_e32 v41, v135, v41
	v_mul_f32_e32 v34, v42, v37
	v_min_f32_e64 v42, -v43, s60
	v_exp_f32_e32 v42, v42
	v_mov_b32_e32 v43, v34
	v_mul_f32_e32 v146, v135, v37
	v_min_f32_e64 v37, -v44, s60
	v_exp_f32_e32 v37, v37
	v_add_f32_e32 v34, 1.0, v42
	v_rcp_f32_e32 v34, v34
	v_add_f32_e32 v44, 1.0, v37
	v_rcp_f32_e32 v44, v44
	v_exp_f32_e32 v45, v45
	v_min_f32_e64 v46, -v46, s60
	v_min_f32_e64 v47, -v47, s60
	v_exp_f32_e32 v46, v46
	v_exp_f32_e32 v47, v47
	v_mul_f32_e32 v42, v42, v34
	v_mul_f32_e32 v147, v135, v34
	v_add_f32_e32 v130, 1.0, v46
	v_mul_f32_e32 v34, v37, v44
	v_add_f32_e32 v37, 1.0, v45
	v_rcp_f32_e32 v37, v37
	v_add_f32_e32 v132, 1.0, v47
	v_rcp_f32_e32 v130, v130
	v_rcp_f32_e32 v132, v132
	v_mul_f32_e32 v44, v135, v44
	v_mul_f32_e32 v45, v45, v37
	v_mul_f32_e32 v37, v135, v37
	v_mul_f32_e32 v46, v46, v130
	v_mul_f32_e32 v47, v47, v132
	v_mul_f32_e32 v34, v34, v45
	v_mul_f32_e32 v134, v46, v47
	v_mul_f32_e32 v134, v34, v134
	v_mov_b32_e32 v148, v134
	v_mov_b32_e32 v240, v134
	s_nop 1
	v_permlane32_swap_b32_e32 v148, v240
	v_cndmask_b32_e64 v148, v148, v240, s[2:3]
	v_mul_f32_e32 v149, v135, v130
	v_mul_f32_e32 v34, v135, v132
	s_waitcnt lgkmcnt(0)
; __device__ __forceinline__ void sb_unit(const Frame& F, int b, int hd, int qi, int dry) {
;     ...
;             float run = C;
;             if (!meta && key0 + 96 < tqw + 31) SB_HALF(96);
;             if (!meta && key0 + 64 < tqw + 31 && __any(run >= SB_DEAD)) SB_HALF(64);
	v_cndmask_b32_e64 v130, 1.0, v148, s[2:3]
	v_mul_f32_e32 v135, v34, v130
	v_mul_f32_e32 v34, v36, v145
	v_mul_f32_e32 v36, v43, v42
	v_mul_f32_e32 v36, v34, v36
	v_mul_f32_e32 v32, v32, v38
	v_mul_f32_e32 v34, v142, v39
	v_mov_b32_e32 v150, v36
	v_mov_b32_e32 v240, v36
	s_nop 1
	v_permlane32_swap_b32_e32 v150, v240
	v_cndmask_b32_e64 v150, v150, v240, s[2:3]
	v_mul_f32_e32 v34, v32, v34
	v_mul_f32_e32 v47, v47, v130
	v_mov_b32_e32 v130, v34
	v_mov_b32_e32 v240, v34
	s_nop 1
	v_permlane32_swap_b32_e32 v130, v240
	v_cndmask_b32_e64 v130, v130, v240, s[2:3]
	v_mul_f32_e32 v46, v46, v47
	v_mul_f32_e32 v32, v134, v148
	s_waitcnt lgkmcnt(1)
	v_mul_f32_e32 v132, v36, v150
	v_mul_f32_e32 v45, v45, v46
	v_mul_f32_e32 v46, v37, v46
	s_waitcnt lgkmcnt(0)
	v_cndmask_b32_e64 v134, 1.0, v130, s[2:3]
	v_pk_mul_f32 v[36:37], v[32:33], v[132:133]
	v_pk_mul_f32 v[34:35], v[34:35], v[130:131]
	v_mul_f32_e32 v132, v36, v134
	v_mul_f32_e32 v134, v39, v132
	v_mul_f32_e32 v142, v142, v134
	v_mul_f32_e32 v148, v38, v142
	v_pk_mul_f32 v[38:39], v[34:35], v[36:37]
	v_mov_b32_e32 v130, v39
	v_mov_b32_e32 v240, v39
	s_nop 1
	v_permlane32_swap_b32_e32 v130, v240
	v_cndmask_b32_e64 v130, v130, v240, s[2:3]
	v_mul_f32_e32 v37, v40, v132
	v_mul_f32_e32 v40, v143, v134
	v_mul_f32_e32 v36, v141, v142
	v_mul_f32_e32 v132, v140, v148
	s_waitcnt lgkmcnt(0)
	v_cndmask_b32_e64 v34, 1.0, v130, s[2:3]
	v_mul_f32_e32 v34, v38, v34
	v_mul_f32_e32 v35, v133, v34
	v_mul_f32_e32 v33, v33, v35
	v_mul_f32_e32 v131, v131, v33
	v_mul_f32_e32 v133, v136, v34
	v_mul_f32_e32 v35, v139, v35
	v_mul_f32_e32 v33, v137, v33
	v_mul_f32_e32 v34, v138, v131
	v_cvt_pk_bf16_f32 v34, v34, v33
	v_cvt_pk_bf16_f32 v35, v35, v133
	v_cvt_pk_bf16_f32 v36, v132, v36
	v_cvt_pk_bf16_f32 v37, v40, v37
	v_cndmask_b32_e64 v33, 1.0, v150, s[2:3]
	v_mul_f32_e32 v32, v32, v33
	v_mfma_f32_32x32x16_bf16 v[16:31], v[92:95], v[34:37], v[16:31]
	v_mul_f32_e32 v33, v42, v32
	v_mul_f32_e32 v42, v43, v33
	v_mul_f32_e32 v43, v145, v42
	v_mul_f32_e32 v47, v149, v47
	v_mul_f32_e32 v40, v44, v45
	v_mul_f32_e32 v44, v147, v32
	v_mul_f32_e32 v33, v146, v33
	v_mfma_f32_32x32x16_bf16 v[0:15], v[88:91], v[34:37], v[0:15]
	v_mul_f32_e32 v32, v41, v42
	v_mul_f32_e32 v34, v144, v43
	v_cvt_pk_bf16_f32 v32, v34, v32
	v_cvt_pk_bf16_f32 v33, v33, v44
	v_cvt_pk_bf16_f32 v34, v40, v46
	v_cvt_pk_bf16_f32 v35, v47, v135
	v_mul_f32_e32 v36, v39, v130
	v_mul_f32_e32 v36, v38, v36
	v_mfma_f32_32x32x16_bf16 v[16:31], v[84:87], v[32:35], v[16:31]
	v_log_f32_e32 v36, v36
	s_nop 0
	v_add_f32_e32 v125, v125, v36
	v_mfma_f32_32x32x16_bf16 v[0:15], v[80:83], v[32:35], v[0:15]
.LBB0_341:
	s_or_b32 s0, s35, 33
	s_cmp_ge_i32 s0, s26
	s_cselect_b64 s[0:1], -1, 0
	s_or_b64 s[0:1], s[18:19], s[0:1]
	s_and_b64 vcc, exec, s[0:1]
	s_cbranch_vccnz .LBB0_344
	v_cmp_le_f32_e32 vcc, s22, v125
	s_cbranch_vccz .LBB0_344
	s_add_i32 s61, s35, 96
	s_cmp_le_i32 s61, s26
	s_cbranch_scc1 .Lsbq_nomask_5
	ds_read_b128 v[32:35], v129 offset:9216
	ds_read_b128 v[214:217], v129 offset:9248
	ds_read_b128 v[210:213], v129 offset:9280
	ds_read_b128 v[130:133], v129 offset:9312
	ds_read_b64_tr_b16 v[92:93], v128 offset:49152
	ds_read_b64_tr_b16 v[94:95], v128 offset:50688
	ds_read_b64_tr_b16 v[90:91], v128 offset:50752
	ds_read_b64_tr_b16 v[88:89], v128 offset:49216
	ds_read_b64_tr_b16 v[84:85], v128 offset:52224
	ds_read_b64_tr_b16 v[86:87], v128 offset:53760
	ds_read_b64_tr_b16 v[82:83], v128 offset:53824
	ds_read_b64_tr_b16 v[80:81], v128 offset:52288
	v_exp_f32_e32 v135, v125
	v_sub_u32_e32 v134, v124, v127
	v_cmp_lt_i32_e32 vcc, 0, v134
	s_waitcnt lgkmcnt(11)
	v_mfma_f32_32x32x16_bf16 v[32:47], v[32:35], v[48:51], 0
	v_cmp_lt_i32_e64 s[0:1], 27, v134
	s_waitcnt lgkmcnt(10)
	v_mfma_f32_32x32x16_bf16 v[32:47], v[214:217], v[52:55], v[32:47]
	s_waitcnt lgkmcnt(9)
	v_mfma_f32_32x32x16_bf16 v[32:47], v[210:213], v[56:59], v[32:47]
	s_waitcnt lgkmcnt(8)
	v_mfma_f32_32x32x16_bf16 v[32:47], v[130:133], v[60:63], v[32:47]
	s_nop 11
	v_min_f32_e64 v32, -v32, s60
	v_min_f32_e64 v33, -v33, s60
	v_exp_f32_e32 v32, v32
	v_min_f32_e64 v34, -v34, s60
	v_exp_f32_e32 v33, v33
	v_exp_f32_e32 v34, v34
	v_min_f32_e64 v35, -v35, s60
	v_exp_f32_e32 v130, v35
	v_add_f32_e32 v35, 1.0, v32
	v_add_f32_e32 v131, 1.0, v33
	v_rcp_f32_e32 v35, v35
	v_add_f32_e32 v132, 1.0, v34
	v_rcp_f32_e32 v131, v131
	v_min_f32_e64 v36, -v36, s60
	v_rcp_f32_e32 v132, v132
	v_exp_f32_e32 v36, v36
	v_add_f32_e32 v133, 1.0, v130
	v_rcp_f32_e32 v136, v133
	v_mul_f32_e32 v32, v32, v35
	v_mul_f32_e32 v133, v135, v35
	v_mul_f32_e32 v33, v33, v131
	v_mul_f32_e32 v137, v135, v131
	v_cndmask_b32_e32 v35, 1.0, v32, vcc
	v_cndmask_b32_e32 v138, 0, v133, vcc
	v_cmp_lt_i32_e32 vcc, 1, v134
	v_mul_f32_e32 v34, v34, v132
	v_mul_f32_e32 v32, v135, v132
	v_cndmask_b32_e32 v131, 1.0, v33, vcc
	v_cndmask_b32_e32 v137, 0, v137, vcc
	v_cmp_lt_i32_e32 vcc, 2, v134
	v_min_f32_e64 v39, -v39, s60
	v_cndmask_b32_e32 v33, 1.0, v34, vcc
	v_add_f32_e32 v34, 1.0, v36
	v_rcp_f32_e32 v34, v34
	v_cndmask_b32_e32 v139, 0, v32, vcc
	v_mul_f32_e32 v32, v130, v136
	v_cmp_lt_i32_e32 vcc, 3, v134
	v_exp_f32_e32 v39, v39
	v_cndmask_b32_e32 v133, 1.0, v32, vcc
	v_mul_f32_e32 v32, v135, v136
	v_cndmask_b32_e32 v136, 0, v32, vcc
	v_mul_f32_e32 v32, v36, v34
	v_min_f32_e64 v36, -v37, s60
	v_exp_f32_e32 v36, v36
	v_cmp_lt_i32_e32 vcc, 8, v134
	v_mul_f32_e32 v34, v135, v34
	v_cndmask_b32_e32 v140, 0, v34, vcc
	v_add_f32_e32 v34, 1.0, v36
	v_rcp_f32_e32 v34, v34
	v_min_f32_e64 v37, -v38, s60
	v_exp_f32_e32 v37, v37
	v_cndmask_b32_e32 v32, 1.0, v32, vcc
	v_mul_f32_e32 v36, v36, v34
	v_cmp_lt_i32_e32 vcc, 9, v134
	v_mul_f32_e32 v34, v135, v34
	v_min_f32_e64 v42, -v42, s60
	v_cndmask_b32_e32 v38, 1.0, v36, vcc
	v_add_f32_e32 v36, 1.0, v37
	v_rcp_f32_e32 v36, v36
	v_cndmask_b32_e32 v141, 0, v34, vcc
	v_cmp_lt_i32_e32 vcc, 10, v134
	v_exp_f32_e32 v42, v42
	v_mul_f32_e32 v34, v37, v36
	v_add_f32_e32 v37, 1.0, v39
	v_rcp_f32_e32 v37, v37
	v_cndmask_b32_e32 v142, 1.0, v34, vcc
	v_mul_f32_e32 v34, v135, v36
	v_cndmask_b32_e32 v143, 0, v34, vcc
	v_mul_f32_e32 v34, v39, v37
	v_cmp_lt_i32_e32 vcc, 11, v134
	v_min_f32_e64 v36, -v40, s60
	v_exp_f32_e32 v36, v36
	v_cndmask_b32_e32 v39, 1.0, v34, vcc
	v_mul_f32_e32 v34, v135, v37
	v_min_f32_e64 v37, -v41, s60
	v_exp_f32_e32 v37, v37
	v_cndmask_b32_e32 v40, 0, v34, vcc
	v_add_f32_e32 v34, 1.0, v36
	v_rcp_f32_e32 v34, v34
	v_add_f32_e32 v41, 1.0, v37
	v_rcp_f32_e32 v41, v41
	v_cmp_lt_i32_e32 vcc, 16, v134
	v_mul_f32_e32 v36, v36, v34
	v_mul_f32_e32 v34, v135, v34
	v_cndmask_b32_e32 v144, 0, v34, vcc
	v_mul_f32_e32 v34, v37, v41
	v_add_f32_e32 v37, 1.0, v42
	v_rcp_f32_e32 v37, v37
	v_cndmask_b32_e32 v36, 1.0, v36, vcc
	v_cmp_lt_i32_e32 vcc, 17, v134
	v_min_f32_e64 v45, -v45, s60
	v_cndmask_b32_e32 v145, 1.0, v34, vcc
	v_mul_f32_e32 v34, v135, v41
	v_cndmask_b32_e32 v41, 0, v34, vcc
	v_mul_f32_e32 v34, v42, v37
	v_cmp_lt_i32_e32 vcc, 18, v134
	v_min_f32_e64 v42, -v43, s60
	v_exp_f32_e32 v42, v42
	v_cndmask_b32_e32 v43, 1.0, v34, vcc
	v_mul_f32_e32 v34, v135, v37
	v_min_f32_e64 v37, -v44, s60
	v_exp_f32_e32 v37, v37
	v_cndmask_b32_e32 v146, 0, v34, vcc
	v_add_f32_e32 v34, 1.0, v42
	v_rcp_f32_e32 v34, v34
	v_add_f32_e32 v44, 1.0, v37
	v_rcp_f32_e32 v44, v44
	v_exp_f32_e32 v45, v45
	v_min_f32_e64 v46, -v46, s60
	v_min_f32_e64 v47, -v47, s60
	v_exp_f32_e32 v46, v46
	v_exp_f32_e32 v47, v47
	v_mul_f32_e32 v42, v42, v34
	v_cmp_lt_i32_e32 vcc, 19, v134
	v_mul_f32_e32 v34, v135, v34
	v_add_f32_e32 v130, 1.0, v46
	v_cndmask_b32_e32 v147, 0, v34, vcc
	v_mul_f32_e32 v34, v37, v44
	v_add_f32_e32 v37, 1.0, v45
	v_rcp_f32_e32 v37, v37
	v_add_f32_e32 v132, 1.0, v47
	v_rcp_f32_e32 v130, v130
	v_rcp_f32_e32 v132, v132
	v_cndmask_b32_e32 v42, 1.0, v42, vcc
	v_cmp_lt_i32_e32 vcc, 24, v134
	v_mul_f32_e32 v44, v135, v44
	v_mul_f32_e32 v45, v45, v37
	v_cndmask_b32_e32 v34, 1.0, v34, vcc
	v_cndmask_b32_e32 v44, 0, v44, vcc
	v_cmp_lt_i32_e32 vcc, 25, v134
	v_mul_f32_e32 v37, v135, v37
	v_mul_f32_e32 v46, v46, v130
	v_cndmask_b32_e32 v45, 1.0, v45, vcc
	v_cndmask_b32_e32 v37, 0, v37, vcc
	v_cmp_lt_i32_e32 vcc, 26, v134
	v_mul_f32_e32 v47, v47, v132
	v_cndmask_b32_e64 v47, 1.0, v47, s[0:1]
	v_cndmask_b32_e32 v46, 1.0, v46, vcc
	v_mul_f32_e32 v34, v34, v45
	v_mul_f32_e32 v134, v46, v47
	v_mul_f32_e32 v134, v34, v134
	v_mov_b32_e32 v148, v134
	v_mov_b32_e32 v240, v134
	s_nop 1
	v_permlane32_swap_b32_e32 v148, v240
	v_cndmask_b32_e64 v148, v148, v240, s[2:3]
	v_mul_f32_e32 v34, v135, v130
	v_cndmask_b32_e32 v149, 0, v34, vcc
	v_mul_f32_e32 v34, v135, v132
	v_cndmask_b32_e64 v34, 0, v34, s[0:1]
	s_waitcnt lgkmcnt(0)
	v_cndmask_b32_e64 v130, 1.0, v148, s[2:3]
	v_mul_f32_e32 v135, v34, v130
	v_mul_f32_e32 v34, v36, v145
	v_mul_f32_e32 v36, v43, v42
	v_mul_f32_e32 v36, v34, v36
	v_mul_f32_e32 v32, v32, v38
	v_mul_f32_e32 v34, v142, v39
	v_mov_b32_e32 v150, v36
	v_mov_b32_e32 v240, v36
	s_nop 1
	v_permlane32_swap_b32_e32 v150, v240
	v_cndmask_b32_e64 v150, v150, v240, s[2:3]
	v_mul_f32_e32 v34, v32, v34
	v_mul_f32_e32 v47, v47, v130
	v_mov_b32_e32 v130, v34
	v_mov_b32_e32 v240, v34
	s_nop 1
	v_permlane32_swap_b32_e32 v130, v240
	v_cndmask_b32_e64 v130, v130, v240, s[2:3]
	v_mul_f32_e32 v46, v46, v47
	v_mul_f32_e32 v32, v134, v148
	s_waitcnt lgkmcnt(1)
	v_mul_f32_e32 v132, v36, v150
	v_mul_f32_e32 v45, v45, v46
	v_mul_f32_e32 v46, v37, v46
	s_waitcnt lgkmcnt(0)
	v_cndmask_b32_e64 v134, 1.0, v130, s[2:3]
	v_pk_mul_f32 v[36:37], v[32:33], v[132:133]
	v_pk_mul_f32 v[34:35], v[34:35], v[130:131]
	v_mul_f32_e32 v132, v36, v134
	v_mul_f32_e32 v134, v39, v132
	v_mul_f32_e32 v142, v142, v134
	v_mul_f32_e32 v148, v38, v142
	v_pk_mul_f32 v[38:39], v[34:35], v[36:37]
	v_mov_b32_e32 v130, v39
	v_mov_b32_e32 v240, v39
	s_nop 1
	v_permlane32_swap_b32_e32 v130, v240
	v_cndmask_b32_e64 v130, v130, v240, s[2:3]
	v_mul_f32_e32 v37, v40, v132
	v_mul_f32_e32 v40, v143, v134
	v_mul_f32_e32 v36, v141, v142
	v_mul_f32_e32 v132, v140, v148
	s_waitcnt lgkmcnt(0)
	v_cndmask_b32_e64 v34, 1.0, v130, s[2:3]
	v_mul_f32_e32 v34, v38, v34
	v_mul_f32_e32 v35, v133, v34
	v_mul_f32_e32 v33, v33, v35
	v_mul_f32_e32 v131, v131, v33
	v_mul_f32_e32 v133, v136, v34
	v_mul_f32_e32 v35, v139, v35
	v_mul_f32_e32 v33, v137, v33
	v_mul_f32_e32 v34, v138, v131
	v_cvt_pk_bf16_f32 v34, v34, v33
	v_cvt_pk_bf16_f32 v35, v35, v133
	v_cvt_pk_bf16_f32 v36, v132, v36
	v_cvt_pk_bf16_f32 v37, v40, v37
	v_cndmask_b32_e64 v33, 1.0, v150, s[2:3]
	v_mul_f32_e32 v32, v32, v33
	v_mfma_f32_32x32x16_bf16 v[16:31], v[92:95], v[34:37], v[16:31]
	v_mul_f32_e32 v33, v42, v32
	v_mul_f32_e32 v42, v43, v33
	v_mul_f32_e32 v43, v145, v42
	v_mul_f32_e32 v47, v149, v47
	v_mul_f32_e32 v40, v44, v45
	v_mul_f32_e32 v44, v147, v32
	v_mul_f32_e32 v33, v146, v33
	v_mfma_f32_32x32x16_bf16 v[0:15], v[88:91], v[34:37], v[0:15]
	v_mul_f32_e32 v32, v41, v42
	v_mul_f32_e32 v34, v144, v43
	v_cvt_pk_bf16_f32 v32, v34, v32
	v_cvt_pk_bf16_f32 v33, v33, v44
	v_cvt_pk_bf16_f32 v34, v40, v46
	v_cvt_pk_bf16_f32 v35, v47, v135
	v_mul_f32_e32 v36, v39, v130
	v_mul_f32_e32 v36, v38, v36
	v_mfma_f32_32x32x16_bf16 v[16:31], v[84:87], v[32:35], v[16:31]
	v_log_f32_e32 v36, v36
	s_nop 0
	v_add_f32_e32 v125, v125, v36
	v_mfma_f32_32x32x16_bf16 v[0:15], v[80:83], v[32:35], v[0:15]
	s_branch .LBB0_344
.Lsbq_nomask_5:
	ds_read_b128 v[32:35], v129 offset:9216
	ds_read_b128 v[214:217], v129 offset:9248
	ds_read_b128 v[210:213], v129 offset:9280
	ds_read_b128 v[130:133], v129 offset:9312
	ds_read_b64_tr_b16 v[92:93], v128 offset:49152
	ds_read_b64_tr_b16 v[94:95], v128 offset:50688
	ds_read_b64_tr_b16 v[90:91], v128 offset:50752
	ds_read_b64_tr_b16 v[88:89], v128 offset:49216
	ds_read_b64_tr_b16 v[84:85], v128 offset:52224
	ds_read_b64_tr_b16 v[86:87], v128 offset:53760
	ds_read_b64_tr_b16 v[82:83], v128 offset:53824
	ds_read_b64_tr_b16 v[80:81], v128 offset:52288
	v_exp_f32_e32 v135, v125
	s_waitcnt lgkmcnt(11)
	v_mfma_f32_32x32x16_bf16 v[32:47], v[32:35], v[48:51], 0
	s_waitcnt lgkmcnt(10)
	v_mfma_f32_32x32x16_bf16 v[32:47], v[214:217], v[52:55], v[32:47]
	s_waitcnt lgkmcnt(9)
	v_mfma_f32_32x32x16_bf16 v[32:47], v[210:213], v[56:59], v[32:47]
	s_waitcnt lgkmcnt(8)
	v_mfma_f32_32x32x16_bf16 v[32:47], v[130:133], v[60:63], v[32:47]
	s_nop 11
	v_min_f32_e64 v32, -v32, s60
	v_min_f32_e64 v33, -v33, s60
	v_exp_f32_e32 v32, v32
	v_min_f32_e64 v34, -v34, s60
	v_exp_f32_e32 v33, v33
	v_exp_f32_e32 v34, v34
	v_min_f32_e64 v35, -v35, s60
	v_exp_f32_e32 v130, v35
	v_add_f32_e32 v35, 1.0, v32
	v_add_f32_e32 v131, 1.0, v33
	v_rcp_f32_e32 v35, v35
	v_add_f32_e32 v132, 1.0, v34
	v_rcp_f32_e32 v131, v131
	v_min_f32_e64 v36, -v36, s60
	v_rcp_f32_e32 v132, v132
	v_exp_f32_e32 v36, v36
	v_add_f32_e32 v133, 1.0, v130
	v_rcp_f32_e32 v136, v133
	v_mul_f32_e32 v32, v32, v35
	v_mul_f32_e32 v138, v135, v35
	v_mul_f32_e32 v33, v33, v131
	v_mul_f32_e32 v137, v135, v131
	v_mov_b32_e32 v35, v32
	v_mul_f32_e32 v34, v34, v132
	v_mul_f32_e32 v139, v135, v132
	v_mov_b32_e32 v131, v33
	v_min_f32_e64 v39, -v39, s60
	v_mov_b32_e32 v33, v34
	v_add_f32_e32 v34, 1.0, v36
	v_rcp_f32_e32 v34, v34
	v_mul_f32_e32 v133, v130, v136
	v_exp_f32_e32 v39, v39
	v_mul_f32_e32 v136, v135, v136
	v_mul_f32_e32 v32, v36, v34
	v_min_f32_e64 v36, -v37, s60
	v_exp_f32_e32 v36, v36
	v_mul_f32_e32 v140, v135, v34
	v_add_f32_e32 v34, 1.0, v36
	v_rcp_f32_e32 v34, v34
	v_min_f32_e64 v37, -v38, s60
	v_exp_f32_e32 v37, v37
	v_mul_f32_e32 v38, v36, v34
	v_mul_f32_e32 v141, v135, v34
	v_min_f32_e64 v42, -v42, s60
	v_add_f32_e32 v36, 1.0, v37
	v_rcp_f32_e32 v36, v36
	v_exp_f32_e32 v42, v42
	v_mul_f32_e32 v142, v37, v36
	v_add_f32_e32 v37, 1.0, v39
	v_rcp_f32_e32 v37, v37
	v_mul_f32_e32 v143, v135, v36
	v_mul_f32_e32 v39, v39, v37
	v_min_f32_e64 v36, -v40, s60
	v_exp_f32_e32 v36, v36
	v_mul_f32_e32 v40, v135, v37
	v_min_f32_e64 v37, -v41, s60
	v_exp_f32_e32 v37, v37
	v_add_f32_e32 v34, 1.0, v36
	v_rcp_f32_e32 v34, v34
	v_add_f32_e32 v41, 1.0, v37
	v_rcp_f32_e32 v41, v41
	v_mul_f32_e32 v36, v36, v34
	v_mul_f32_e32 v144, v135, v34
	v_mul_f32_e32 v145, v37, v41
	v_add_f32_e32 v37, 1.0, v42
	v_rcp_f32_e32 v37, v37
	v_min_f32_e64 v45, -v45, s60
	v_mul_f32_e32 v41, v135, v41
	v_mul_f32_e32 v34, v42, v37
	v_min_f32_e64 v42, -v43, s60
	v_exp_f32_e32 v42, v42
	v_mov_b32_e32 v43, v34
	v_mul_f32_e32 v146, v135, v37
	v_min_f32_e64 v37, -v44, s60
	v_exp_f32_e32 v37, v37
	v_add_f32_e32 v34, 1.0, v42
	v_rcp_f32_e32 v34, v34
	v_add_f32_e32 v44, 1.0, v37
	v_rcp_f32_e32 v44, v44
	v_exp_f32_e32 v45, v45
	v_min_f32_e64 v46, -v46, s60
	v_min_f32_e64 v47, -v47, s60
	v_exp_f32_e32 v46, v46
	v_exp_f32_e32 v47, v47
	v_mul_f32_e32 v42, v42, v34
	v_mul_f32_e32 v147, v135, v34
	v_add_f32_e32 v130, 1.0, v46
	v_mul_f32_e32 v34, v37, v44
	v_add_f32_e32 v37, 1.0, v45
	v_rcp_f32_e32 v37, v37
	v_add_f32_e32 v132, 1.0, v47
	v_rcp_f32_e32 v130, v130
	v_rcp_f32_e32 v132, v132
	v_mul_f32_e32 v44, v135, v44
	v_mul_f32_e32 v45, v45, v37
	v_mul_f32_e32 v37, v135, v37
	v_mul_f32_e32 v46, v46, v130
	v_mul_f32_e32 v47, v47, v132
	v_mul_f32_e32 v34, v34, v45
	v_mul_f32_e32 v134, v46, v47
	v_mul_f32_e32 v134, v34, v134
	v_mov_b32_e32 v148, v134
	v_mov_b32_e32 v240, v134
	s_nop 1
	v_permlane32_swap_b32_e32 v148, v240
	v_cndmask_b32_e64 v148, v148, v240, s[2:3]
	v_mul_f32_e32 v149, v135, v130
	v_mul_f32_e32 v34, v135, v132
	s_waitcnt lgkmcnt(0)
	v_cndmask_b32_e64 v130, 1.0, v148, s[2:3]
	v_mul_f32_e32 v135, v34, v130
	v_mul_f32_e32 v34, v36, v145
	v_mul_f32_e32 v36, v43, v42
	v_mul_f32_e32 v36, v34, v36
	v_mul_f32_e32 v32, v32, v38
	v_mul_f32_e32 v34, v142, v39
	v_mov_b32_e32 v150, v36
	v_mov_b32_e32 v240, v36
	s_nop 1
	v_permlane32_swap_b32_e32 v150, v240
	v_cndmask_b32_e64 v150, v150, v240, s[2:3]
	v_mul_f32_e32 v34, v32, v34
	v_mul_f32_e32 v47, v47, v130
	v_mov_b32_e32 v130, v34
	v_mov_b32_e32 v240, v34
	s_nop 1
	v_permlane32_swap_b32_e32 v130, v240
	v_cndmask_b32_e64 v130, v130, v240, s[2:3]
	v_mul_f32_e32 v46, v46, v47
	v_mul_f32_e32 v32, v134, v148
	s_waitcnt lgkmcnt(1)
	v_mul_f32_e32 v132, v36, v150
	v_mul_f32_e32 v45, v45, v46
	v_mul_f32_e32 v46, v37, v46
	s_waitcnt lgkmcnt(0)
	v_cndmask_b32_e64 v134, 1.0, v130, s[2:3]
	v_pk_mul_f32 v[36:37], v[32:33], v[132:133]
	v_pk_mul_f32 v[34:35], v[34:35], v[130:131]
	v_mul_f32_e32 v132, v36, v134
	v_mul_f32_e32 v134, v39, v132
	v_mul_f32_e32 v142, v142, v134
	v_mul_f32_e32 v148, v38, v142
	v_pk_mul_f32 v[38:39], v[34:35], v[36:37]
	v_mov_b32_e32 v130, v39
	v_mov_b32_e32 v240, v39
	s_nop 1
	v_permlane32_swap_b32_e32 v130, v240
	v_cndmask_b32_e64 v130, v130, v240, s[2:3]
	v_mul_f32_e32 v37, v40, v132
	v_mul_f32_e32 v40, v143, v134
	v_mul_f32_e32 v36, v141, v142
	v_mul_f32_e32 v132, v140, v148
	s_waitcnt lgkmcnt(0)
	v_cndmask_b32_e64 v34, 1.0, v130, s[2:3]
	v_mul_f32_e32 v34, v38, v34
	v_mul_f32_e32 v35, v133, v34
	v_mul_f32_e32 v33, v33, v35
	v_mul_f32_e32 v131, v131, v33
	v_mul_f32_e32 v133, v136, v34
	v_mul_f32_e32 v35, v139, v35
	v_mul_f32_e32 v33, v137, v33
	v_mul_f32_e32 v34, v138, v131
	v_cvt_pk_bf16_f32 v34, v34, v33
	v_cvt_pk_bf16_f32 v35, v35, v133
	v_cvt_pk_bf16_f32 v36, v132, v36
	v_cvt_pk_bf16_f32 v37, v40, v37
	v_cndmask_b32_e64 v33, 1.0, v150, s[2:3]
	v_mul_f32_e32 v32, v32, v33
	v_mfma_f32_32x32x16_bf16 v[16:31], v[92:95], v[34:37], v[16:31]
	v_mul_f32_e32 v33, v42, v32
	v_mul_f32_e32 v42, v43, v33
	v_mul_f32_e32 v43, v145, v42
	v_mul_f32_e32 v47, v149, v47
	v_mul_f32_e32 v40, v44, v45
	v_mul_f32_e32 v44, v147, v32
	v_mul_f32_e32 v33, v146, v33
	v_mfma_f32_32x32x16_bf16 v[0:15], v[88:91], v[34:37], v[0:15]
	v_mul_f32_e32 v32, v41, v42
	v_mul_f32_e32 v34, v144, v43
	v_cvt_pk_bf16_f32 v32, v34, v32
	v_cvt_pk_bf16_f32 v33, v33, v44
	v_cvt_pk_bf16_f32 v34, v40, v46
	v_cvt_pk_bf16_f32 v35, v47, v135
	v_mul_f32_e32 v36, v39, v130
	v_mul_f32_e32 v36, v38, v36
	v_mfma_f32_32x32x16_bf16 v[16:31], v[84:87], v[32:35], v[16:31]
	v_log_f32_e32 v36, v36
	s_nop 0
	v_add_f32_e32 v125, v125, v36
	v_mfma_f32_32x32x16_bf16 v[0:15], v[80:83], v[32:35], v[0:15]
; __device__ __forceinline__ void sb_unit(const Frame& F, int b, int hd, int qi, int dry) {
;     ...
;             float run = C;
;             if (!meta && key0 + 96 < tqw + 31) SB_HALF(96);
;             if (!meta && key0 + 64 < tqw + 31 && __any(run >= SB_DEAD)) SB_HALF(64);
;             if (!meta && key0 + 32 < tqw + 31 && __any(run >= SB_DEAD)) SB_HALF(32);
.LBB0_344:
	s_or_b32 s0, s35, 1
	s_cmp_ge_i32 s0, s26
	s_cselect_b64 s[0:1], -1, 0
	s_or_b64 s[0:1], s[18:19], s[0:1]
	s_and_b64 vcc, exec, s[0:1]
	s_cbranch_vccnz .LBB0_347
	v_cmp_le_f32_e32 vcc, s22, v125
	s_cbranch_vccz .LBB0_347
	s_add_i32 s61, s35, 64
	s_cmp_le_i32 s61, s26
	s_cbranch_scc1 .Lsbq_nomask_4
	ds_read_b128 v[32:35], v129 offset:4608
	ds_read_b128 v[214:217], v129 offset:4640
	ds_read_b128 v[210:213], v129 offset:4672
	ds_read_b128 v[130:133], v129 offset:4704
	ds_read_b64_tr_b16 v[92:93], v128 offset:43008
	ds_read_b64_tr_b16 v[94:95], v128 offset:44544
	ds_read_b64_tr_b16 v[90:91], v128 offset:44608
	ds_read_b64_tr_b16 v[88:89], v128 offset:43072
	ds_read_b64_tr_b16 v[84:85], v128 offset:46080
	ds_read_b64_tr_b16 v[86:87], v128 offset:47616
	ds_read_b64_tr_b16 v[82:83], v128 offset:47680
	ds_read_b64_tr_b16 v[80:81], v128 offset:46144
	v_exp_f32_e32 v135, v125
	v_sub_u32_e32 v134, v126, v127
	v_cmp_lt_i32_e32 vcc, 0, v134
	s_waitcnt lgkmcnt(11)
	v_mfma_f32_32x32x16_bf16 v[32:47], v[32:35], v[48:51], 0
	v_cmp_lt_i32_e64 s[0:1], 27, v134
	s_waitcnt lgkmcnt(10)
	v_mfma_f32_32x32x16_bf16 v[32:47], v[214:217], v[52:55], v[32:47]
	s_waitcnt lgkmcnt(9)
	v_mfma_f32_32x32x16_bf16 v[32:47], v[210:213], v[56:59], v[32:47]
	s_waitcnt lgkmcnt(8)
	v_mfma_f32_32x32x16_bf16 v[32:47], v[130:133], v[60:63], v[32:47]
	s_nop 11
	v_min_f32_e64 v32, -v32, s60
	v_min_f32_e64 v33, -v33, s60
	v_exp_f32_e32 v32, v32
	v_min_f32_e64 v34, -v34, s60
	v_exp_f32_e32 v33, v33
	v_exp_f32_e32 v34, v34
	v_min_f32_e64 v35, -v35, s60
	v_exp_f32_e32 v130, v35
	v_add_f32_e32 v35, 1.0, v32
	v_add_f32_e32 v131, 1.0, v33
	v_rcp_f32_e32 v35, v35
	v_add_f32_e32 v132, 1.0, v34
	v_rcp_f32_e32 v131, v131
	v_min_f32_e64 v36, -v36, s60
	v_rcp_f32_e32 v132, v132
	v_exp_f32_e32 v36, v36
	v_add_f32_e32 v133, 1.0, v130
	v_rcp_f32_e32 v136, v133
	v_mul_f32_e32 v32, v32, v35
	v_mul_f32_e32 v133, v135, v35
	v_mul_f32_e32 v33, v33, v131
	v_mul_f32_e32 v137, v135, v131
	v_cndmask_b32_e32 v35, 1.0, v32, vcc
	v_cndmask_b32_e32 v138, 0, v133, vcc
	v_cmp_lt_i32_e32 vcc, 1, v134
	v_mul_f32_e32 v34, v34, v132
	v_mul_f32_e32 v32, v135, v132
	v_cndmask_b32_e32 v131, 1.0, v33, vcc
	v_cndmask_b32_e32 v137, 0, v137, vcc
	v_cmp_lt_i32_e32 vcc, 2, v134
	v_min_f32_e64 v39, -v39, s60
	v_cndmask_b32_e32 v33, 1.0, v34, vcc
	v_add_f32_e32 v34, 1.0, v36
	v_rcp_f32_e32 v34, v34
	v_cndmask_b32_e32 v139, 0, v32, vcc
	v_mul_f32_e32 v32, v130, v136
	v_cmp_lt_i32_e32 vcc, 3, v134
	v_exp_f32_e32 v39, v39
	v_cndmask_b32_e32 v133, 1.0, v32, vcc
	v_mul_f32_e32 v32, v135, v136
	v_cndmask_b32_e32 v136, 0, v32, vcc
	v_mul_f32_e32 v32, v36, v34
	v_min_f32_e64 v36, -v37, s60
	v_exp_f32_e32 v36, v36
	v_cmp_lt_i32_e32 vcc, 8, v134
	v_mul_f32_e32 v34, v135, v34
	v_cndmask_b32_e32 v140, 0, v34, vcc
	v_add_f32_e32 v34, 1.0, v36
	v_rcp_f32_e32 v34, v34
	v_min_f32_e64 v37, -v38, s60
	v_exp_f32_e32 v37, v37
	v_cndmask_b32_e32 v32, 1.0, v32, vcc
	v_mul_f32_e32 v36, v36, v34
	v_cmp_lt_i32_e32 vcc, 9, v134
	v_mul_f32_e32 v34, v135, v34
	v_min_f32_e64 v42, -v42, s60
	v_cndmask_b32_e32 v38, 1.0, v36, vcc
	v_add_f32_e32 v36, 1.0, v37
	v_rcp_f32_e32 v36, v36
	v_cndmask_b32_e32 v141, 0, v34, vcc
	v_cmp_lt_i32_e32 vcc, 10, v134
	v_exp_f32_e32 v42, v42
	v_mul_f32_e32 v34, v37, v36
	v_add_f32_e32 v37, 1.0, v39
	v_rcp_f32_e32 v37, v37
	v_cndmask_b32_e32 v142, 1.0, v34, vcc
	v_mul_f32_e32 v34, v135, v36
	v_cndmask_b32_e32 v143, 0, v34, vcc
	v_mul_f32_e32 v34, v39, v37
	v_cmp_lt_i32_e32 vcc, 11, v134
	v_min_f32_e64 v36, -v40, s60
	v_exp_f32_e32 v36, v36
	v_cndmask_b32_e32 v39, 1.0, v34, vcc
	v_mul_f32_e32 v34, v135, v37
	v_min_f32_e64 v37, -v41, s60
	v_exp_f32_e32 v37, v37
	v_cndmask_b32_e32 v40, 0, v34, vcc
	v_add_f32_e32 v34, 1.0, v36
	v_rcp_f32_e32 v34, v34
	v_add_f32_e32 v41, 1.0, v37
	v_rcp_f32_e32 v41, v41
	v_cmp_lt_i32_e32 vcc, 16, v134
	v_mul_f32_e32 v36, v36, v34
	v_mul_f32_e32 v34, v135, v34
	v_cndmask_b32_e32 v144, 0, v34, vcc
	v_mul_f32_e32 v34, v37, v41
	v_add_f32_e32 v37, 1.0, v42
	v_rcp_f32_e32 v37, v37
	v_cndmask_b32_e32 v36, 1.0, v36, vcc
	v_cmp_lt_i32_e32 vcc, 17, v134
	v_min_f32_e64 v45, -v45, s60
	v_cndmask_b32_e32 v145, 1.0, v34, vcc
	v_mul_f32_e32 v34, v135, v41
	v_cndmask_b32_e32 v41, 0, v34, vcc
	v_mul_f32_e32 v34, v42, v37
	v_cmp_lt_i32_e32 vcc, 18, v134
	v_min_f32_e64 v42, -v43, s60
	v_exp_f32_e32 v42, v42
	v_cndmask_b32_e32 v43, 1.0, v34, vcc
	v_mul_f32_e32 v34, v135, v37
	v_min_f32_e64 v37, -v44, s60
	v_exp_f32_e32 v37, v37
	v_cndmask_b32_e32 v146, 0, v34, vcc
	v_add_f32_e32 v34, 1.0, v42
	v_rcp_f32_e32 v34, v34
	v_add_f32_e32 v44, 1.0, v37
	v_rcp_f32_e32 v44, v44
	v_exp_f32_e32 v45, v45
	v_min_f32_e64 v46, -v46, s60
	v_min_f32_e64 v47, -v47, s60
	v_exp_f32_e32 v46, v46
	v_exp_f32_e32 v47, v47
	v_mul_f32_e32 v42, v42, v34
	v_cmp_lt_i32_e32 vcc, 19, v134
	v_mul_f32_e32 v34, v135, v34
	v_add_f32_e32 v130, 1.0, v46
	v_cndmask_b32_e32 v147, 0, v34, vcc
	v_mul_f32_e32 v34, v37, v44
	v_add_f32_e32 v37, 1.0, v45
	v_rcp_f32_e32 v37, v37
	v_add_f32_e32 v132, 1.0, v47
	v_rcp_f32_e32 v130, v130
	v_rcp_f32_e32 v132, v132
	v_cndmask_b32_e32 v42, 1.0, v42, vcc
	v_cmp_lt_i32_e32 vcc, 24, v134
	v_mul_f32_e32 v44, v135, v44
	v_mul_f32_e32 v45, v45, v37
	v_cndmask_b32_e32 v34, 1.0, v34, vcc
	v_cndmask_b32_e32 v44, 0, v44, vcc
	v_cmp_lt_i32_e32 vcc, 25, v134
	v_mul_f32_e32 v37, v135, v37
	v_mul_f32_e32 v46, v46, v130
	v_cndmask_b32_e32 v45, 1.0, v45, vcc
	v_cndmask_b32_e32 v37, 0, v37, vcc
	v_cmp_lt_i32_e32 vcc, 26, v134
	v_mul_f32_e32 v47, v47, v132
	v_cndmask_b32_e64 v47, 1.0, v47, s[0:1]
	v_cndmask_b32_e32 v46, 1.0, v46, vcc
	v_mul_f32_e32 v34, v34, v45
	v_mul_f32_e32 v134, v46, v47
	v_mul_f32_e32 v134, v34, v134
	v_mov_b32_e32 v148, v134
	v_mov_b32_e32 v240, v134
	s_nop 1
	v_permlane32_swap_b32_e32 v148, v240
	v_cndmask_b32_e64 v148, v148, v240, s[2:3]
	v_mul_f32_e32 v34, v135, v130
	v_cndmask_b32_e32 v149, 0, v34, vcc
	v_mul_f32_e32 v34, v135, v132
	v_cndmask_b32_e64 v34, 0, v34, s[0:1]
	s_waitcnt lgkmcnt(0)
	v_cndmask_b32_e64 v130, 1.0, v148, s[2:3]
	v_mul_f32_e32 v135, v34, v130
	v_mul_f32_e32 v34, v36, v145
	v_mul_f32_e32 v36, v43, v42
	v_mul_f32_e32 v36, v34, v36
	v_mul_f32_e32 v32, v32, v38
	v_mul_f32_e32 v34, v142, v39
	v_mov_b32_e32 v150, v36
	v_mov_b32_e32 v240, v36
	s_nop 1
	v_permlane32_swap_b32_e32 v150, v240
	v_cndmask_b32_e64 v150, v150, v240, s[2:3]
	v_mul_f32_e32 v34, v32, v34
	v_mul_f32_e32 v47, v47, v130
	v_mov_b32_e32 v130, v34
	v_mov_b32_e32 v240, v34
	s_nop 1
	v_permlane32_swap_b32_e32 v130, v240
	v_cndmask_b32_e64 v130, v130, v240, s[2:3]
	v_mul_f32_e32 v46, v46, v47
	v_mul_f32_e32 v32, v134, v148
	s_waitcnt lgkmcnt(1)
	v_mul_f32_e32 v132, v36, v150
	v_mul_f32_e32 v45, v45, v46
	v_mul_f32_e32 v46, v37, v46
	s_waitcnt lgkmcnt(0)
	v_cndmask_b32_e64 v134, 1.0, v130, s[2:3]
	v_pk_mul_f32 v[36:37], v[32:33], v[132:133]
	v_pk_mul_f32 v[34:35], v[34:35], v[130:131]
	v_mul_f32_e32 v132, v36, v134
	v_mul_f32_e32 v134, v39, v132
	v_mul_f32_e32 v142, v142, v134
	v_mul_f32_e32 v148, v38, v142
	v_pk_mul_f32 v[38:39], v[34:35], v[36:37]
	v_mov_b32_e32 v130, v39
	v_mov_b32_e32 v240, v39
	s_nop 1
	v_permlane32_swap_b32_e32 v130, v240
	v_cndmask_b32_e64 v130, v130, v240, s[2:3]
	v_mul_f32_e32 v37, v40, v132
	v_mul_f32_e32 v40, v143, v134
	v_mul_f32_e32 v36, v141, v142
	v_mul_f32_e32 v132, v140, v148
	s_waitcnt lgkmcnt(0)
	v_cndmask_b32_e64 v34, 1.0, v130, s[2:3]
	v_mul_f32_e32 v34, v38, v34
	v_mul_f32_e32 v35, v133, v34
	v_mul_f32_e32 v33, v33, v35
	v_mul_f32_e32 v131, v131, v33
	v_mul_f32_e32 v133, v136, v34
	v_mul_f32_e32 v35, v139, v35
	v_mul_f32_e32 v33, v137, v33
	v_mul_f32_e32 v34, v138, v131
	v_cvt_pk_bf16_f32 v34, v34, v33
	v_cvt_pk_bf16_f32 v35, v35, v133
	v_cvt_pk_bf16_f32 v36, v132, v36
	v_cvt_pk_bf16_f32 v37, v40, v37
	v_cndmask_b32_e64 v33, 1.0, v150, s[2:3]
	v_mul_f32_e32 v32, v32, v33
	v_mfma_f32_32x32x16_bf16 v[16:31], v[92:95], v[34:37], v[16:31]
	v_mul_f32_e32 v33, v42, v32
	v_mul_f32_e32 v42, v43, v33
	v_mul_f32_e32 v43, v145, v42
	v_mul_f32_e32 v47, v149, v47
	v_mul_f32_e32 v40, v44, v45
	v_mul_f32_e32 v44, v147, v32
	v_mul_f32_e32 v33, v146, v33
	v_mfma_f32_32x32x16_bf16 v[0:15], v[88:91], v[34:37], v[0:15]
	v_mul_f32_e32 v32, v41, v42
	v_mul_f32_e32 v34, v144, v43
	v_cvt_pk_bf16_f32 v32, v34, v32
	v_cvt_pk_bf16_f32 v33, v33, v44
	v_cvt_pk_bf16_f32 v34, v40, v46
	v_cvt_pk_bf16_f32 v35, v47, v135
	v_mul_f32_e32 v36, v39, v130
	v_mul_f32_e32 v36, v38, v36
	v_mfma_f32_32x32x16_bf16 v[16:31], v[84:87], v[32:35], v[16:31]
	v_log_f32_e32 v36, v36
	s_nop 0
	v_add_f32_e32 v125, v125, v36
	v_mfma_f32_32x32x16_bf16 v[0:15], v[80:83], v[32:35], v[0:15]
	s_branch .LBB0_347
.Lsbq_nomask_4:
	ds_read_b128 v[32:35], v129 offset:4608
	ds_read_b128 v[214:217], v129 offset:4640
	ds_read_b128 v[210:213], v129 offset:4672
	ds_read_b128 v[130:133], v129 offset:4704
	ds_read_b64_tr_b16 v[92:93], v128 offset:43008
	ds_read_b64_tr_b16 v[94:95], v128 offset:44544
	ds_read_b64_tr_b16 v[90:91], v128 offset:44608
	ds_read_b64_tr_b16 v[88:89], v128 offset:43072
	ds_read_b64_tr_b16 v[84:85], v128 offset:46080
	ds_read_b64_tr_b16 v[86:87], v128 offset:47616
	ds_read_b64_tr_b16 v[82:83], v128 offset:47680
	ds_read_b64_tr_b16 v[80:81], v128 offset:46144
	v_exp_f32_e32 v135, v125
	s_waitcnt lgkmcnt(11)
	v_mfma_f32_32x32x16_bf16 v[32:47], v[32:35], v[48:51], 0
	s_waitcnt lgkmcnt(10)
	v_mfma_f32_32x32x16_bf16 v[32:47], v[214:217], v[52:55], v[32:47]
	s_waitcnt lgkmcnt(9)
	v_mfma_f32_32x32x16_bf16 v[32:47], v[210:213], v[56:59], v[32:47]
	s_waitcnt lgkmcnt(8)
	v_mfma_f32_32x32x16_bf16 v[32:47], v[130:133], v[60:63], v[32:47]
	s_nop 11
	v_min_f32_e64 v32, -v32, s60
	v_min_f32_e64 v33, -v33, s60
	v_exp_f32_e32 v32, v32
	v_min_f32_e64 v34, -v34, s60
	v_exp_f32_e32 v33, v33
	v_exp_f32_e32 v34, v34
	v_min_f32_e64 v35, -v35, s60
	v_exp_f32_e32 v130, v35
	v_add_f32_e32 v35, 1.0, v32
	v_add_f32_e32 v131, 1.0, v33
	v_rcp_f32_e32 v35, v35
	v_add_f32_e32 v132, 1.0, v34
	v_rcp_f32_e32 v131, v131
	v_min_f32_e64 v36, -v36, s60
	v_rcp_f32_e32 v132, v132
	v_exp_f32_e32 v36, v36
	v_add_f32_e32 v133, 1.0, v130
	v_rcp_f32_e32 v136, v133
	v_mul_f32_e32 v32, v32, v35
	v_mul_f32_e32 v138, v135, v35
	v_mul_f32_e32 v33, v33, v131
	v_mul_f32_e32 v137, v135, v131
	v_mov_b32_e32 v35, v32
	v_mul_f32_e32 v34, v34, v132
	v_mul_f32_e32 v139, v135, v132
	v_mov_b32_e32 v131, v33
	v_min_f32_e64 v39, -v39, s60
	v_mov_b32_e32 v33, v34
	v_add_f32_e32 v34, 1.0, v36
	v_rcp_f32_e32 v34, v34
	v_mul_f32_e32 v133, v130, v136
	v_exp_f32_e32 v39, v39
	v_mul_f32_e32 v136, v135, v136
	v_mul_f32_e32 v32, v36, v34
	v_min_f32_e64 v36, -v37, s60
	v_exp_f32_e32 v36, v36
	v_mul_f32_e32 v140, v135, v34
	v_add_f32_e32 v34, 1.0, v36
	v_rcp_f32_e32 v34, v34
	v_min_f32_e64 v37, -v38, s60
	v_exp_f32_e32 v37, v37
	v_mul_f32_e32 v38, v36, v34
	v_mul_f32_e32 v141, v135, v34
	v_min_f32_e64 v42, -v42, s60
	v_add_f32_e32 v36, 1.0, v37
	v_rcp_f32_e32 v36, v36
	v_exp_f32_e32 v42, v42
	v_mul_f32_e32 v142, v37, v36
	v_add_f32_e32 v37, 1.0, v39
	v_rcp_f32_e32 v37, v37
	v_mul_f32_e32 v143, v135, v36
	v_mul_f32_e32 v39, v39, v37
	v_min_f32_e64 v36, -v40, s60
	v_exp_f32_e32 v36, v36
	v_mul_f32_e32 v40, v135, v37
	v_min_f32_e64 v37, -v41, s60
	v_exp_f32_e32 v37, v37
	v_add_f32_e32 v34, 1.0, v36
	v_rcp_f32_e32 v34, v34
	v_add_f32_e32 v41, 1.0, v37
	v_rcp_f32_e32 v41, v41
	v_mul_f32_e32 v36, v36, v34
	v_mul_f32_e32 v144, v135, v34
	v_mul_f32_e32 v145, v37, v41
	v_add_f32_e32 v37, 1.0, v42
	v_rcp_f32_e32 v37, v37
	v_min_f32_e64 v45, -v45, s60
	v_mul_f32_e32 v41, v135, v41
	v_mul_f32_e32 v34, v42, v37
	v_min_f32_e64 v42, -v43, s60
	v_exp_f32_e32 v42, v42
	v_mov_b32_e32 v43, v34
	v_mul_f32_e32 v146, v135, v37
	v_min_f32_e64 v37, -v44, s60
	v_exp_f32_e32 v37, v37
	v_add_f32_e32 v34, 1.0, v42
	v_rcp_f32_e32 v34, v34
	v_add_f32_e32 v44, 1.0, v37
	v_rcp_f32_e32 v44, v44
	v_exp_f32_e32 v45, v45
	v_min_f32_e64 v46, -v46, s60
	v_min_f32_e64 v47, -v47, s60
	v_exp_f32_e32 v46, v46
	v_exp_f32_e32 v47, v47
	v_mul_f32_e32 v42, v42, v34
	v_mul_f32_e32 v147, v135, v34
	v_add_f32_e32 v130, 1.0, v46
	v_mul_f32_e32 v34, v37, v44
	v_add_f32_e32 v37, 1.0, v45
	v_rcp_f32_e32 v37, v37
	v_add_f32_e32 v132, 1.0, v47
	v_rcp_f32_e32 v130, v130
	v_rcp_f32_e32 v132, v132
	v_mul_f32_e32 v44, v135, v44
	v_mul_f32_e32 v45, v45, v37
	v_mul_f32_e32 v37, v135, v37
	v_mul_f32_e32 v46, v46, v130
	v_mul_f32_e32 v47, v47, v132
	v_mul_f32_e32 v34, v34, v45
	v_mul_f32_e32 v134, v46, v47
	v_mul_f32_e32 v134, v34, v134
	v_mov_b32_e32 v148, v134
	v_mov_b32_e32 v240, v134
	s_nop 1
	v_permlane32_swap_b32_e32 v148, v240
	v_cndmask_b32_e64 v148, v148, v240, s[2:3]
	v_mul_f32_e32 v149, v135, v130
	v_mul_f32_e32 v34, v135, v132
	s_waitcnt lgkmcnt(0)
	v_cndmask_b32_e64 v130, 1.0, v148, s[2:3]
	v_mul_f32_e32 v135, v34, v130
	v_mul_f32_e32 v34, v36, v145
	v_mul_f32_e32 v36, v43, v42
	v_mul_f32_e32 v36, v34, v36
	v_mul_f32_e32 v32, v32, v38
	v_mul_f32_e32 v34, v142, v39
	v_mov_b32_e32 v150, v36
	v_mov_b32_e32 v240, v36
	s_nop 1
	v_permlane32_swap_b32_e32 v150, v240
	v_cndmask_b32_e64 v150, v150, v240, s[2:3]
	v_mul_f32_e32 v34, v32, v34
	v_mul_f32_e32 v47, v47, v130
	v_mov_b32_e32 v130, v34
	v_mov_b32_e32 v240, v34
	s_nop 1
	v_permlane32_swap_b32_e32 v130, v240
	v_cndmask_b32_e64 v130, v130, v240, s[2:3]
	v_mul_f32_e32 v46, v46, v47
	v_mul_f32_e32 v32, v134, v148
	s_waitcnt lgkmcnt(1)
	v_mul_f32_e32 v132, v36, v150
	v_mul_f32_e32 v45, v45, v46
	v_mul_f32_e32 v46, v37, v46
	s_waitcnt lgkmcnt(0)
	v_cndmask_b32_e64 v134, 1.0, v130, s[2:3]
	v_pk_mul_f32 v[36:37], v[32:33], v[132:133]
	v_pk_mul_f32 v[34:35], v[34:35], v[130:131]
	v_mul_f32_e32 v132, v36, v134
	v_mul_f32_e32 v134, v39, v132
	v_mul_f32_e32 v142, v142, v134
	v_mul_f32_e32 v148, v38, v142
	v_pk_mul_f32 v[38:39], v[34:35], v[36:37]
	v_mov_b32_e32 v130, v39
	v_mov_b32_e32 v240, v39
	s_nop 1
	v_permlane32_swap_b32_e32 v130, v240
	v_cndmask_b32_e64 v130, v130, v240, s[2:3]
	v_mul_f32_e32 v37, v40, v132
	v_mul_f32_e32 v40, v143, v134
	v_mul_f32_e32 v36, v141, v142
	v_mul_f32_e32 v132, v140, v148
	s_waitcnt lgkmcnt(0)
	v_cndmask_b32_e64 v34, 1.0, v130, s[2:3]
	v_mul_f32_e32 v34, v38, v34
	v_mul_f32_e32 v35, v133, v34
	v_mul_f32_e32 v33, v33, v35
	v_mul_f32_e32 v131, v131, v33
	v_mul_f32_e32 v133, v136, v34
	v_mul_f32_e32 v35, v139, v35
	v_mul_f32_e32 v33, v137, v33
	v_mul_f32_e32 v34, v138, v131
	v_cvt_pk_bf16_f32 v34, v34, v33
	v_cvt_pk_bf16_f32 v35, v35, v133
	v_cvt_pk_bf16_f32 v36, v132, v36
	v_cvt_pk_bf16_f32 v37, v40, v37
	v_cndmask_b32_e64 v33, 1.0, v150, s[2:3]
	v_mul_f32_e32 v32, v32, v33
	v_mfma_f32_32x32x16_bf16 v[16:31], v[92:95], v[34:37], v[16:31]
	v_mul_f32_e32 v33, v42, v32
	v_mul_f32_e32 v42, v43, v33
	v_mul_f32_e32 v43, v145, v42
	v_mul_f32_e32 v47, v149, v47
	v_mul_f32_e32 v40, v44, v45
	v_mul_f32_e32 v44, v147, v32
	v_mul_f32_e32 v33, v146, v33
	v_mfma_f32_32x32x16_bf16 v[0:15], v[88:91], v[34:37], v[0:15]
	v_mul_f32_e32 v32, v41, v42
	v_mul_f32_e32 v34, v144, v43
	v_cvt_pk_bf16_f32 v32, v34, v32
	v_cvt_pk_bf16_f32 v33, v33, v44
	v_cvt_pk_bf16_f32 v34, v40, v46
	v_cvt_pk_bf16_f32 v35, v47, v135
	v_mul_f32_e32 v36, v39, v130
	v_mul_f32_e32 v36, v38, v36
	v_mfma_f32_32x32x16_bf16 v[16:31], v[84:87], v[32:35], v[16:31]
	v_log_f32_e32 v36, v36
	s_nop 0
	v_add_f32_e32 v125, v125, v36
	v_mfma_f32_32x32x16_bf16 v[0:15], v[80:83], v[32:35], v[0:15]

; #define LAS __attribute__((address_space(3)))
; #define S_LOAD(key0) do { st0 = *(const u32x4*)(kg + (size_t)(key0) * 1024); st1 = *(const u32x4*)(kg + (size_t)((key0) + 64) * 1024); st2 = *(const u32x4*)(vg + (size_t)(key0) * 1024); st3 = *(const u32x4*)(vg + (size_t)((key0) + 64) * 1024); } while (0)
; __device__ __forceinline__ void sb_unit(const Frame& F, int b, int hd, int qi, int dry) {
;     ...
;     for (int it = 0; it < nt; ++it) {
;         const bool meta = (it > jmax);
;         const int key0 = meta ? 0 : NMETA + 128 * (jmax - it);
;         if (it + 1 < nt) { const int nk = (it + 1 > jmax) ? 0 : NMETA + 128 * (jmax - it - 1); S_LOAD(nk); }
;         if (!dead && (meta || key0 < tqw + 31)) {
;             const LAS unsigned char* kb = lds + kra + (it & 1) * SK_BUF;
;             const LAS unsigned char* vb = lds + vra + (it & 1) * SV_BUF;
.LBB0_360:
	s_xor_b64 s[0:1], s[0:1], -1
	s_andn2_b64 vcc, exec, s[0:1]
	s_mov_b64 s[0:1], -1
	s_cbranch_vccnz .LBB0_373
	s_add_i32 s34, s31, 0xffffff10
	s_cmp_gt_u32 s35, s27
	s_cselect_b64 s[18:19], -1, 0
	s_and_b64 s[0:1], s[18:19], exec
	s_cselect_b32 s34, 0, s34
	s_cmp_lt_i32 s34, s29
	s_cselect_b64 s[0:1], -1, 0
	s_or_b64 s[0:1], s[18:19], s[0:1]
	s_andn2_b64 vcc, exec, s[0:1]
	s_mov_b64 s[0:1], 0
	s_cbranch_vccnz .LBB0_373
	s_and_b32 s0, s35, 1
	s_mul_i32 s35, s0, 0x4800
	s_mul_i32 s36, s0, 0x6000
	s_or_b32 s0, s34, 0x41
	s_cmp_ge_i32 s0, s25
	s_cselect_b64 s[0:1], -1, 0
	s_or_b64 s[0:1], s[18:19], s[0:1]
	s_and_b64 vcc, exec, s[0:1]
	v_add_u32_e32 v129, s35, v118
	v_or_b32_e32 v127, s34, v205
	v_add_u32_e32 v128, s36, v119
	s_cbranch_vccnz .LBB0_364
	s_add_i32 s61, s34, 128
	s_cmp_le_i32 s61, s25
	s_cbranch_scc1 .Lsbq_nomask_3
	ds_read_b128 v[32:35], v129 offset:13824
	ds_read_b128 v[214:217], v129 offset:13856
	ds_read_b128 v[210:213], v129 offset:13888
	ds_read_b128 v[130:133], v129 offset:13920
	ds_read_b64_tr_b16 v[92:93], v128 offset:55296
	ds_read_b64_tr_b16 v[94:95], v128 offset:56832
	ds_read_b64_tr_b16 v[90:91], v128 offset:56896
	ds_read_b64_tr_b16 v[88:89], v128 offset:55360
	ds_read_b64_tr_b16 v[84:85], v128 offset:58368
	ds_read_b64_tr_b16 v[86:87], v128 offset:59904
	ds_read_b64_tr_b16 v[82:83], v128 offset:59968
	ds_read_b64_tr_b16 v[80:81], v128 offset:58432
	v_exp_f32_e32 v135, v126
	v_sub_u32_e32 v134, v115, v127
	v_cmp_lt_i32_e32 vcc, 0, v134
	s_waitcnt lgkmcnt(11)
	v_mfma_f32_32x32x16_bf16 v[32:47], v[32:35], v[48:51], 0
	v_cmp_lt_i32_e64 s[0:1], 27, v134
	s_waitcnt lgkmcnt(10)
	v_mfma_f32_32x32x16_bf16 v[32:47], v[214:217], v[52:55], v[32:47]
	s_waitcnt lgkmcnt(9)
	v_mfma_f32_32x32x16_bf16 v[32:47], v[210:213], v[56:59], v[32:47]
	s_waitcnt lgkmcnt(8)
	v_mfma_f32_32x32x16_bf16 v[32:47], v[130:133], v[60:63], v[32:47]
	s_nop 11
	v_min_f32_e64 v32, -v32, s60
	v_min_f32_e64 v33, -v33, s60
	v_exp_f32_e32 v32, v32
	v_min_f32_e64 v34, -v34, s60
	v_exp_f32_e32 v33, v33
	v_exp_f32_e32 v34, v34
	v_min_f32_e64 v35, -v35, s60
	v_exp_f32_e32 v130, v35
	v_add_f32_e32 v35, 1.0, v32
	v_add_f32_e32 v131, 1.0, v33
	v_rcp_f32_e32 v35, v35
	v_add_f32_e32 v132, 1.0, v34
	v_rcp_f32_e32 v131, v131
	v_min_f32_e64 v36, -v36, s60
	v_rcp_f32_e32 v132, v132
	v_exp_f32_e32 v36, v36
	v_add_f32_e32 v133, 1.0, v130
	v_rcp_f32_e32 v136, v133
	v_mul_f32_e32 v32, v32, v35
	v_mul_f32_e32 v133, v135, v35
	v_mul_f32_e32 v33, v33, v131
	v_mul_f32_e32 v137, v135, v131
	v_cndmask_b32_e32 v35, 1.0, v32, vcc
	v_cndmask_b32_e32 v138, 0, v133, vcc
	v_cmp_lt_i32_e32 vcc, 1, v134
	v_mul_f32_e32 v34, v34, v132
	v_mul_f32_e32 v32, v135, v132
	v_cndmask_b32_e32 v131, 1.0, v33, vcc
	v_cndmask_b32_e32 v137, 0, v137, vcc
	v_cmp_lt_i32_e32 vcc, 2, v134
	v_min_f32_e64 v39, -v39, s60
	v_cndmask_b32_e32 v33, 1.0, v34, vcc
	v_add_f32_e32 v34, 1.0, v36
	v_rcp_f32_e32 v34, v34
	v_cndmask_b32_e32 v139, 0, v32, vcc
	v_mul_f32_e32 v32, v130, v136
	v_cmp_lt_i32_e32 vcc, 3, v134
	v_exp_f32_e32 v39, v39
	v_cndmask_b32_e32 v133, 1.0, v32, vcc
	v_mul_f32_e32 v32, v135, v136
	v_cndmask_b32_e32 v136, 0, v32, vcc
	v_mul_f32_e32 v32, v36, v34
	v_min_f32_e64 v36, -v37, s60
	v_exp_f32_e32 v36, v36
	v_cmp_lt_i32_e32 vcc, 8, v134
	v_mul_f32_e32 v34, v135, v34
	v_cndmask_b32_e32 v140, 0, v34, vcc
	v_add_f32_e32 v34, 1.0, v36
	v_rcp_f32_e32 v34, v34
	v_min_f32_e64 v37, -v38, s60
	v_exp_f32_e32 v37, v37
	v_cndmask_b32_e32 v32, 1.0, v32, vcc
	v_mul_f32_e32 v36, v36, v34
	v_cmp_lt_i32_e32 vcc, 9, v134
	v_mul_f32_e32 v34, v135, v34
	v_min_f32_e64 v42, -v42, s60
	v_cndmask_b32_e32 v38, 1.0, v36, vcc
	v_add_f32_e32 v36, 1.0, v37
	v_rcp_f32_e32 v36, v36
	v_cndmask_b32_e32 v141, 0, v34, vcc
	v_cmp_lt_i32_e32 vcc, 10, v134
	v_exp_f32_e32 v42, v42
	v_mul_f32_e32 v34, v37, v36
	v_add_f32_e32 v37, 1.0, v39
	v_rcp_f32_e32 v37, v37
	v_cndmask_b32_e32 v142, 1.0, v34, vcc
	v_mul_f32_e32 v34, v135, v36
	v_cndmask_b32_e32 v143, 0, v34, vcc
	v_mul_f32_e32 v34, v39, v37
	v_cmp_lt_i32_e32 vcc, 11, v134
	v_min_f32_e64 v36, -v40, s60
	v_exp_f32_e32 v36, v36
	v_cndmask_b32_e32 v39, 1.0, v34, vcc
	v_mul_f32_e32 v34, v135, v37
	v_min_f32_e64 v37, -v41, s60
	v_exp_f32_e32 v37, v37
	v_cndmask_b32_e32 v40, 0, v34, vcc
	v_add_f32_e32 v34, 1.0, v36
	v_rcp_f32_e32 v34, v34
	v_add_f32_e32 v41, 1.0, v37
	v_rcp_f32_e32 v41, v41
	v_cmp_lt_i32_e32 vcc, 16, v134
	v_mul_f32_e32 v36, v36, v34
	v_mul_f32_e32 v34, v135, v34
	v_cndmask_b32_e32 v144, 0, v34, vcc
	v_mul_f32_e32 v34, v37, v41
	v_add_f32_e32 v37, 1.0, v42
	v_rcp_f32_e32 v37, v37
	v_cndmask_b32_e32 v36, 1.0, v36, vcc
	v_cmp_lt_i32_e32 vcc, 17, v134
	v_min_f32_e64 v45, -v45, s60
	v_cndmask_b32_e32 v145, 1.0, v34, vcc
	v_mul_f32_e32 v34, v135, v41
	v_cndmask_b32_e32 v41, 0, v34, vcc
	v_mul_f32_e32 v34, v42, v37
	v_cmp_lt_i32_e32 vcc, 18, v134
	v_min_f32_e64 v42, -v43, s60
	v_exp_f32_e32 v42, v42
	v_cndmask_b32_e32 v43, 1.0, v34, vcc
	v_mul_f32_e32 v34, v135, v37
	v_min_f32_e64 v37, -v44, s60
	v_exp_f32_e32 v37, v37
	v_cndmask_b32_e32 v146, 0, v34, vcc
	v_add_f32_e32 v34, 1.0, v42
	v_rcp_f32_e32 v34, v34
	v_add_f32_e32 v44, 1.0, v37
	v_rcp_f32_e32 v44, v44
	v_exp_f32_e32 v45, v45
	v_min_f32_e64 v46, -v46, s60
	v_min_f32_e64 v47, -v47, s60
	v_exp_f32_e32 v46, v46
	v_exp_f32_e32 v47, v47
	v_mul_f32_e32 v42, v42, v34
	v_cmp_lt_i32_e32 vcc, 19, v134
	v_mul_f32_e32 v34, v135, v34
	v_add_f32_e32 v130, 1.0, v46
	v_cndmask_b32_e32 v147, 0, v34, vcc
	v_mul_f32_e32 v34, v37, v44
	v_add_f32_e32 v37, 1.0, v45
	v_rcp_f32_e32 v37, v37
	v_add_f32_e32 v132, 1.0, v47
	v_rcp_f32_e32 v130, v130
	v_rcp_f32_e32 v132, v132
	v_cndmask_b32_e32 v42, 1.0, v42, vcc
	v_cmp_lt_i32_e32 vcc, 24, v134
	v_mul_f32_e32 v44, v135, v44
	v_mul_f32_e32 v45, v45, v37
	v_cndmask_b32_e32 v34, 1.0, v34, vcc
	v_cndmask_b32_e32 v44, 0, v44, vcc
	v_cmp_lt_i32_e32 vcc, 25, v134
	v_mul_f32_e32 v37, v135, v37
	v_mul_f32_e32 v46, v46, v130
	v_cndmask_b32_e32 v45, 1.0, v45, vcc
	v_cndmask_b32_e32 v37, 0, v37, vcc
	v_cmp_lt_i32_e32 vcc, 26, v134
	v_mul_f32_e32 v47, v47, v132
	v_cndmask_b32_e64 v47, 1.0, v47, s[0:1]
	v_cndmask_b32_e32 v46, 1.0, v46, vcc
	v_mul_f32_e32 v34, v34, v45
	v_mul_f32_e32 v134, v46, v47
	v_mul_f32_e32 v134, v34, v134
	v_mov_b32_e32 v148, v134
	v_mov_b32_e32 v240, v134
	s_nop 1
	v_permlane32_swap_b32_e32 v148, v240
	v_cndmask_b32_e64 v148, v148, v240, s[2:3]
	v_mul_f32_e32 v34, v135, v130
	v_cndmask_b32_e32 v149, 0, v34, vcc
	v_mul_f32_e32 v34, v135, v132
	v_cndmask_b32_e64 v34, 0, v34, s[0:1]
	s_waitcnt lgkmcnt(0)
	v_cndmask_b32_e64 v130, 1.0, v148, s[2:3]
	v_mul_f32_e32 v135, v34, v130
	v_mul_f32_e32 v34, v36, v145
	v_mul_f32_e32 v36, v43, v42
	v_mul_f32_e32 v36, v34, v36
	v_mul_f32_e32 v32, v32, v38
	v_mul_f32_e32 v34, v142, v39
	v_mov_b32_e32 v150, v36
	v_mov_b32_e32 v240, v36
	s_nop 1
	v_permlane32_swap_b32_e32 v150, v240
	v_cndmask_b32_e64 v150, v150, v240, s[2:3]
	v_mul_f32_e32 v34, v32, v34
	v_mul_f32_e32 v47, v47, v130
	v_mov_b32_e32 v130, v34
	v_mov_b32_e32 v240, v34
	s_nop 1
	v_permlane32_swap_b32_e32 v130, v240
	v_cndmask_b32_e64 v130, v130, v240, s[2:3]
	v_mul_f32_e32 v46, v46, v47
	v_mul_f32_e32 v32, v134, v148
	s_waitcnt lgkmcnt(1)
	v_mul_f32_e32 v132, v36, v150
	v_mul_f32_e32 v45, v45, v46
	v_mul_f32_e32 v46, v37, v46
	s_waitcnt lgkmcnt(0)
	v_cndmask_b32_e64 v134, 1.0, v130, s[2:3]
	v_pk_mul_f32 v[36:37], v[32:33], v[132:133]
	v_pk_mul_f32 v[34:35], v[34:35], v[130:131]
	v_mul_f32_e32 v132, v36, v134
	v_mul_f32_e32 v134, v39, v132
	v_mul_f32_e32 v142, v142, v134
	v_mul_f32_e32 v148, v38, v142
	v_pk_mul_f32 v[38:39], v[34:35], v[36:37]
	v_mov_b32_e32 v130, v39
	v_mov_b32_e32 v240, v39
	s_nop 1
	v_permlane32_swap_b32_e32 v130, v240
	v_cndmask_b32_e64 v130, v130, v240, s[2:3]
	v_mul_f32_e32 v37, v40, v132
	v_mul_f32_e32 v40, v143, v134
	v_mul_f32_e32 v36, v141, v142
	v_mul_f32_e32 v132, v140, v148
	s_waitcnt lgkmcnt(0)
	v_cndmask_b32_e64 v34, 1.0, v130, s[2:3]
	v_mul_f32_e32 v34, v38, v34
	v_mul_f32_e32 v35, v133, v34
	v_mul_f32_e32 v33, v33, v35
	v_mul_f32_e32 v131, v131, v33
	v_mul_f32_e32 v133, v136, v34
	v_mul_f32_e32 v35, v139, v35
	v_mul_f32_e32 v33, v137, v33
	v_mul_f32_e32 v34, v138, v131
	v_cvt_pk_bf16_f32 v34, v34, v33
	v_cvt_pk_bf16_f32 v35, v35, v133
	v_cvt_pk_bf16_f32 v36, v132, v36
	v_cvt_pk_bf16_f32 v37, v40, v37
	v_cndmask_b32_e64 v33, 1.0, v150, s[2:3]
	v_mul_f32_e32 v32, v32, v33
	v_mfma_f32_32x32x16_bf16 v[0:15], v[92:95], v[34:37], v[0:15]
	v_mul_f32_e32 v33, v42, v32
	v_mul_f32_e32 v42, v43, v33
	v_mul_f32_e32 v43, v145, v42
	v_mul_f32_e32 v47, v149, v47
	v_mul_f32_e32 v40, v44, v45
	v_mul_f32_e32 v44, v147, v32
	v_mul_f32_e32 v33, v146, v33
	v_mfma_f32_32x32x16_bf16 v[16:31], v[88:91], v[34:37], v[16:31]
	v_mul_f32_e32 v32, v41, v42
	v_mul_f32_e32 v34, v144, v43
	v_cvt_pk_bf16_f32 v32, v34, v32
	v_cvt_pk_bf16_f32 v33, v33, v44
	v_cvt_pk_bf16_f32 v34, v40, v46
	v_cvt_pk_bf16_f32 v35, v47, v135
	v_mul_f32_e32 v36, v39, v130
	v_mul_f32_e32 v36, v38, v36
	v_mfma_f32_32x32x16_bf16 v[0:15], v[84:87], v[32:35], v[0:15]
	v_log_f32_e32 v36, v36
	s_nop 0
	v_add_f32_e32 v126, v126, v36
	v_mfma_f32_32x32x16_bf16 v[16:31], v[80:83], v[32:35], v[16:31]
	s_branch .LBB0_364
.Lsbq_nomask_3:
	ds_read_b128 v[32:35], v129 offset:13824
	ds_read_b128 v[214:217], v129 offset:13856
	ds_read_b128 v[210:213], v129 offset:13888
	ds_read_b128 v[130:133], v129 offset:13920
	ds_read_b64_tr_b16 v[92:93], v128 offset:55296
	ds_read_b64_tr_b16 v[94:95], v128 offset:56832
	ds_read_b64_tr_b16 v[90:91], v128 offset:56896
	ds_read_b64_tr_b16 v[88:89], v128 offset:55360
	ds_read_b64_tr_b16 v[84:85], v128 offset:58368
	ds_read_b64_tr_b16 v[86:87], v128 offset:59904
	ds_read_b64_tr_b16 v[82:83], v128 offset:59968
	ds_read_b64_tr_b16 v[80:81], v128 offset:58432
	v_exp_f32_e32 v135, v126
	s_waitcnt lgkmcnt(11)
	v_mfma_f32_32x32x16_bf16 v[32:47], v[32:35], v[48:51], 0
	s_waitcnt lgkmcnt(10)
	v_mfma_f32_32x32x16_bf16 v[32:47], v[214:217], v[52:55], v[32:47]
	s_waitcnt lgkmcnt(9)
	v_mfma_f32_32x32x16_bf16 v[32:47], v[210:213], v[56:59], v[32:47]
	s_waitcnt lgkmcnt(8)
	v_mfma_f32_32x32x16_bf16 v[32:47], v[130:133], v[60:63], v[32:47]
	s_nop 11
	v_min_f32_e64 v32, -v32, s60
	v_min_f32_e64 v33, -v33, s60
	v_exp_f32_e32 v32, v32
	v_min_f32_e64 v34, -v34, s60
	v_exp_f32_e32 v33, v33
	v_exp_f32_e32 v34, v34
	v_min_f32_e64 v35, -v35, s60
	v_exp_f32_e32 v130, v35
	v_add_f32_e32 v35, 1.0, v32
	v_add_f32_e32 v131, 1.0, v33
	v_rcp_f32_e32 v35, v35
	v_add_f32_e32 v132, 1.0, v34
	v_rcp_f32_e32 v131, v131
	v_min_f32_e64 v36, -v36, s60
	v_rcp_f32_e32 v132, v132
	v_exp_f32_e32 v36, v36
	v_add_f32_e32 v133, 1.0, v130
	v_rcp_f32_e32 v136, v133
	v_mul_f32_e32 v32, v32, v35
	v_mul_f32_e32 v138, v135, v35
	v_mul_f32_e32 v33, v33, v131
	v_mul_f32_e32 v137, v135, v131
	v_mov_b32_e32 v35, v32
	v_mul_f32_e32 v34, v34, v132
	v_mul_f32_e32 v139, v135, v132
	v_mov_b32_e32 v131, v33
	v_min_f32_e64 v39, -v39, s60
	v_mov_b32_e32 v33, v34
	v_add_f32_e32 v34, 1.0, v36
	v_rcp_f32_e32 v34, v34
	v_mul_f32_e32 v133, v130, v136
	v_exp_f32_e32 v39, v39
	v_mul_f32_e32 v136, v135, v136
	v_mul_f32_e32 v32, v36, v34
	v_min_f32_e64 v36, -v37, s60
	v_exp_f32_e32 v36, v36
	v_mul_f32_e32 v140, v135, v34
	v_add_f32_e32 v34, 1.0, v36
	v_rcp_f32_e32 v34, v34
	v_min_f32_e64 v37, -v38, s60
	v_exp_f32_e32 v37, v37
	v_mul_f32_e32 v38, v36, v34
	v_mul_f32_e32 v141, v135, v34
	v_min_f32_e64 v42, -v42, s60
	v_add_f32_e32 v36, 1.0, v37
	v_rcp_f32_e32 v36, v36
	v_exp_f32_e32 v42, v42
	v_mul_f32_e32 v142, v37, v36
	v_add_f32_e32 v37, 1.0, v39
	v_rcp_f32_e32 v37, v37
	v_mul_f32_e32 v143, v135, v36
	v_mul_f32_e32 v39, v39, v37
	v_min_f32_e64 v36, -v40, s60
	v_exp_f32_e32 v36, v36
	v_mul_f32_e32 v40, v135, v37
	v_min_f32_e64 v37, -v41, s60
	v_exp_f32_e32 v37, v37
	v_add_f32_e32 v34, 1.0, v36
	v_rcp_f32_e32 v34, v34
	v_add_f32_e32 v41, 1.0, v37
	v_rcp_f32_e32 v41, v41
	v_mul_f32_e32 v36, v36, v34
	v_mul_f32_e32 v144, v135, v34
	v_mul_f32_e32 v145, v37, v41
	v_add_f32_e32 v37, 1.0, v42
	v_rcp_f32_e32 v37, v37
	v_min_f32_e64 v45, -v45, s60
	v_mul_f32_e32 v41, v135, v41
	v_mul_f32_e32 v34, v42, v37
	v_min_f32_e64 v42, -v43, s60
	v_exp_f32_e32 v42, v42
	v_mov_b32_e32 v43, v34
	v_mul_f32_e32 v146, v135, v37
	v_min_f32_e64 v37, -v44, s60
	v_exp_f32_e32 v37, v37
	v_add_f32_e32 v34, 1.0, v42
	v_rcp_f32_e32 v34, v34
	v_add_f32_e32 v44, 1.0, v37
	v_rcp_f32_e32 v44, v44
	v_exp_f32_e32 v45, v45
	v_min_f32_e64 v46, -v46, s60
	v_min_f32_e64 v47, -v47, s60
	v_exp_f32_e32 v46, v46
	v_exp_f32_e32 v47, v47
	v_mul_f32_e32 v42, v42, v34
	v_mul_f32_e32 v147, v135, v34
	v_add_f32_e32 v130, 1.0, v46
	v_mul_f32_e32 v34, v37, v44
	v_add_f32_e32 v37, 1.0, v45
	v_rcp_f32_e32 v37, v37
	v_add_f32_e32 v132, 1.0, v47
	v_rcp_f32_e32 v130, v130
	v_rcp_f32_e32 v132, v132
	v_mul_f32_e32 v44, v135, v44
	v_mul_f32_e32 v45, v45, v37
	v_mul_f32_e32 v37, v135, v37
	v_mul_f32_e32 v46, v46, v130
	v_mul_f32_e32 v47, v47, v132
	v_mul_f32_e32 v34, v34, v45
	v_mul_f32_e32 v134, v46, v47
	v_mul_f32_e32 v134, v34, v134
	v_mov_b32_e32 v148, v134
	v_mov_b32_e32 v240, v134
	s_nop 1
	v_permlane32_swap_b32_e32 v148, v240
	v_cndmask_b32_e64 v148, v148, v240, s[2:3]
	v_mul_f32_e32 v149, v135, v130
	v_mul_f32_e32 v34, v135, v132
	s_waitcnt lgkmcnt(0)
; __device__ __forceinline__ void sb_unit(const Frame& F, int b, int hd, int qi, int dry) {
;     ...
;             float run = C;
;             if (!meta && key0 + 96 < tqw + 31) SB_HALF(96);
;             if (!meta && key0 + 64 < tqw + 31 && __any(run >= SB_DEAD)) SB_HALF(64);
	v_cndmask_b32_e64 v130, 1.0, v148, s[2:3]
	v_mul_f32_e32 v135, v34, v130
	v_mul_f32_e32 v34, v36, v145
	v_mul_f32_e32 v36, v43, v42
	v_mul_f32_e32 v36, v34, v36
	v_mul_f32_e32 v32, v32, v38
	v_mul_f32_e32 v34, v142, v39
	v_mov_b32_e32 v150, v36
	v_mov_b32_e32 v240, v36
	s_nop 1
	v_permlane32_swap_b32_e32 v150, v240
	v_cndmask_b32_e64 v150, v150, v240, s[2:3]
	v_mul_f32_e32 v34, v32, v34
	v_mul_f32_e32 v47, v47, v130
	v_mov_b32_e32 v130, v34
	v_mov_b32_e32 v240, v34
	s_nop 1
	v_permlane32_swap_b32_e32 v130, v240
	v_cndmask_b32_e64 v130, v130, v240, s[2:3]
	v_mul_f32_e32 v46, v46, v47
	v_mul_f32_e32 v32, v134, v148
	s_waitcnt lgkmcnt(1)
	v_mul_f32_e32 v132, v36, v150
	v_mul_f32_e32 v45, v45, v46
	v_mul_f32_e32 v46, v37, v46
	s_waitcnt lgkmcnt(0)
	v_cndmask_b32_e64 v134, 1.0, v130, s[2:3]
	v_pk_mul_f32 v[36:37], v[32:33], v[132:133]
	v_pk_mul_f32 v[34:35], v[34:35], v[130:131]
	v_mul_f32_e32 v132, v36, v134
	v_mul_f32_e32 v134, v39, v132
	v_mul_f32_e32 v142, v142, v134
	v_mul_f32_e32 v148, v38, v142
	v_pk_mul_f32 v[38:39], v[34:35], v[36:37]
	v_mov_b32_e32 v130, v39
	v_mov_b32_e32 v240, v39
	s_nop 1
	v_permlane32_swap_b32_e32 v130, v240
	v_cndmask_b32_e64 v130, v130, v240, s[2:3]
	v_mul_f32_e32 v37, v40, v132
	v_mul_f32_e32 v40, v143, v134
	v_mul_f32_e32 v36, v141, v142
	v_mul_f32_e32 v132, v140, v148
	s_waitcnt lgkmcnt(0)
	v_cndmask_b32_e64 v34, 1.0, v130, s[2:3]
	v_mul_f32_e32 v34, v38, v34
	v_mul_f32_e32 v35, v133, v34
	v_mul_f32_e32 v33, v33, v35
	v_mul_f32_e32 v131, v131, v33
	v_mul_f32_e32 v133, v136, v34
	v_mul_f32_e32 v35, v139, v35
	v_mul_f32_e32 v33, v137, v33
	v_mul_f32_e32 v34, v138, v131
	v_cvt_pk_bf16_f32 v34, v34, v33
	v_cvt_pk_bf16_f32 v35, v35, v133
	v_cvt_pk_bf16_f32 v36, v132, v36
	v_cvt_pk_bf16_f32 v37, v40, v37
	v_cndmask_b32_e64 v33, 1.0, v150, s[2:3]
	v_mul_f32_e32 v32, v32, v33
	v_mfma_f32_32x32x16_bf16 v[0:15], v[92:95], v[34:37], v[0:15]
	v_mul_f32_e32 v33, v42, v32
	v_mul_f32_e32 v42, v43, v33
	v_mul_f32_e32 v43, v145, v42
	v_mul_f32_e32 v47, v149, v47
	v_mul_f32_e32 v40, v44, v45
	v_mul_f32_e32 v44, v147, v32
	v_mul_f32_e32 v33, v146, v33
	v_mfma_f32_32x32x16_bf16 v[16:31], v[88:91], v[34:37], v[16:31]
	v_mul_f32_e32 v32, v41, v42
	v_mul_f32_e32 v34, v144, v43
	v_cvt_pk_bf16_f32 v32, v34, v32
	v_cvt_pk_bf16_f32 v33, v33, v44
	v_cvt_pk_bf16_f32 v34, v40, v46
	v_cvt_pk_bf16_f32 v35, v47, v135
	v_mul_f32_e32 v36, v39, v130
	v_mul_f32_e32 v36, v38, v36
	v_mfma_f32_32x32x16_bf16 v[0:15], v[84:87], v[32:35], v[0:15]
	v_log_f32_e32 v36, v36
	s_nop 0
	v_add_f32_e32 v126, v126, v36
	v_mfma_f32_32x32x16_bf16 v[16:31], v[80:83], v[32:35], v[16:31]
.LBB0_364:
	s_or_b32 s0, s34, 33
	s_cmp_ge_i32 s0, s25
	s_cselect_b64 s[0:1], -1, 0
	s_or_b64 s[0:1], s[18:19], s[0:1]
	s_and_b64 vcc, exec, s[0:1]
	s_cbranch_vccnz .LBB0_367
	v_cmp_le_f32_e32 vcc, s22, v126
	s_cbranch_vccz .LBB0_367
	s_add_i32 s61, s34, 96
	s_cmp_le_i32 s61, s25
	s_cbranch_scc1 .Lsbq_nomask_2
	ds_read_b128 v[32:35], v129 offset:9216
	ds_read_b128 v[214:217], v129 offset:9248
	ds_read_b128 v[210:213], v129 offset:9280
	ds_read_b128 v[130:133], v129 offset:9312
	ds_read_b64_tr_b16 v[92:93], v128 offset:49152
	ds_read_b64_tr_b16 v[94:95], v128 offset:50688
	ds_read_b64_tr_b16 v[90:91], v128 offset:50752
	ds_read_b64_tr_b16 v[88:89], v128 offset:49216
	ds_read_b64_tr_b16 v[84:85], v128 offset:52224
	ds_read_b64_tr_b16 v[86:87], v128 offset:53760
	ds_read_b64_tr_b16 v[82:83], v128 offset:53824
	ds_read_b64_tr_b16 v[80:81], v128 offset:52288
	v_exp_f32_e32 v135, v126
	v_sub_u32_e32 v134, v124, v127
	v_cmp_lt_i32_e32 vcc, 0, v134
	s_waitcnt lgkmcnt(11)
	v_mfma_f32_32x32x16_bf16 v[32:47], v[32:35], v[48:51], 0
	v_cmp_lt_i32_e64 s[0:1], 27, v134
	s_waitcnt lgkmcnt(10)
	v_mfma_f32_32x32x16_bf16 v[32:47], v[214:217], v[52:55], v[32:47]
	s_waitcnt lgkmcnt(9)
	v_mfma_f32_32x32x16_bf16 v[32:47], v[210:213], v[56:59], v[32:47]
	s_waitcnt lgkmcnt(8)
	v_mfma_f32_32x32x16_bf16 v[32:47], v[130:133], v[60:63], v[32:47]
	s_nop 11
	v_min_f32_e64 v32, -v32, s60
	v_min_f32_e64 v33, -v33, s60
	v_exp_f32_e32 v32, v32
	v_min_f32_e64 v34, -v34, s60
	v_exp_f32_e32 v33, v33
	v_exp_f32_e32 v34, v34
	v_min_f32_e64 v35, -v35, s60
	v_exp_f32_e32 v130, v35
	v_add_f32_e32 v35, 1.0, v32
	v_add_f32_e32 v131, 1.0, v33
	v_rcp_f32_e32 v35, v35
	v_add_f32_e32 v132, 1.0, v34
	v_rcp_f32_e32 v131, v131
	v_min_f32_e64 v36, -v36, s60
	v_rcp_f32_e32 v132, v132
	v_exp_f32_e32 v36, v36
	v_add_f32_e32 v133, 1.0, v130
	v_rcp_f32_e32 v136, v133
	v_mul_f32_e32 v32, v32, v35
	v_mul_f32_e32 v133, v135, v35
	v_mul_f32_e32 v33, v33, v131
	v_mul_f32_e32 v137, v135, v131
	v_cndmask_b32_e32 v35, 1.0, v32, vcc
	v_cndmask_b32_e32 v138, 0, v133, vcc
	v_cmp_lt_i32_e32 vcc, 1, v134
	v_mul_f32_e32 v34, v34, v132
	v_mul_f32_e32 v32, v135, v132
	v_cndmask_b32_e32 v131, 1.0, v33, vcc
	v_cndmask_b32_e32 v137, 0, v137, vcc
	v_cmp_lt_i32_e32 vcc, 2, v134
	v_min_f32_e64 v39, -v39, s60
	v_cndmask_b32_e32 v33, 1.0, v34, vcc
	v_add_f32_e32 v34, 1.0, v36
	v_rcp_f32_e32 v34, v34
	v_cndmask_b32_e32 v139, 0, v32, vcc
	v_mul_f32_e32 v32, v130, v136
	v_cmp_lt_i32_e32 vcc, 3, v134
	v_exp_f32_e32 v39, v39
	v_cndmask_b32_e32 v133, 1.0, v32, vcc
	v_mul_f32_e32 v32, v135, v136
	v_cndmask_b32_e32 v136, 0, v32, vcc
	v_mul_f32_e32 v32, v36, v34
	v_min_f32_e64 v36, -v37, s60
	v_exp_f32_e32 v36, v36
	v_cmp_lt_i32_e32 vcc, 8, v134
	v_mul_f32_e32 v34, v135, v34
	v_cndmask_b32_e32 v140, 0, v34, vcc
	v_add_f32_e32 v34, 1.0, v36
	v_rcp_f32_e32 v34, v34
	v_min_f32_e64 v37, -v38, s60
	v_exp_f32_e32 v37, v37
	v_cndmask_b32_e32 v32, 1.0, v32, vcc
	v_mul_f32_e32 v36, v36, v34
	v_cmp_lt_i32_e32 vcc, 9, v134
	v_mul_f32_e32 v34, v135, v34
	v_min_f32_e64 v42, -v42, s60
	v_cndmask_b32_e32 v38, 1.0, v36, vcc
	v_add_f32_e32 v36, 1.0, v37
	v_rcp_f32_e32 v36, v36
	v_cndmask_b32_e32 v141, 0, v34, vcc
	v_cmp_lt_i32_e32 vcc, 10, v134
	v_exp_f32_e32 v42, v42
	v_mul_f32_e32 v34, v37, v36
	v_add_f32_e32 v37, 1.0, v39
	v_rcp_f32_e32 v37, v37
	v_cndmask_b32_e32 v142, 1.0, v34, vcc
	v_mul_f32_e32 v34, v135, v36
	v_cndmask_b32_e32 v143, 0, v34, vcc
	v_mul_f32_e32 v34, v39, v37
	v_cmp_lt_i32_e32 vcc, 11, v134
	v_min_f32_e64 v36, -v40, s60
	v_exp_f32_e32 v36, v36
	v_cndmask_b32_e32 v39, 1.0, v34, vcc
	v_mul_f32_e32 v34, v135, v37
	v_min_f32_e64 v37, -v41, s60
	v_exp_f32_e32 v37, v37
	v_cndmask_b32_e32 v40, 0, v34, vcc
	v_add_f32_e32 v34, 1.0, v36
	v_rcp_f32_e32 v34, v34
	v_add_f32_e32 v41, 1.0, v37
	v_rcp_f32_e32 v41, v41
	v_cmp_lt_i32_e32 vcc, 16, v134
	v_mul_f32_e32 v36, v36, v34
	v_mul_f32_e32 v34, v135, v34
	v_cndmask_b32_e32 v144, 0, v34, vcc
	v_mul_f32_e32 v34, v37, v41
	v_add_f32_e32 v37, 1.0, v42
	v_rcp_f32_e32 v37, v37
	v_cndmask_b32_e32 v36, 1.0, v36, vcc
	v_cmp_lt_i32_e32 vcc, 17, v134
	v_min_f32_e64 v45, -v45, s60
	v_cndmask_b32_e32 v145, 1.0, v34, vcc
	v_mul_f32_e32 v34, v135, v41
	v_cndmask_b32_e32 v41, 0, v34, vcc
	v_mul_f32_e32 v34, v42, v37
	v_cmp_lt_i32_e32 vcc, 18, v134
	v_min_f32_e64 v42, -v43, s60
	v_exp_f32_e32 v42, v42
	v_cndmask_b32_e32 v43, 1.0, v34, vcc
	v_mul_f32_e32 v34, v135, v37
	v_min_f32_e64 v37, -v44, s60
	v_exp_f32_e32 v37, v37
	v_cndmask_b32_e32 v146, 0, v34, vcc
	v_add_f32_e32 v34, 1.0, v42
	v_rcp_f32_e32 v34, v34
	v_add_f32_e32 v44, 1.0, v37
	v_rcp_f32_e32 v44, v44
	v_exp_f32_e32 v45, v45
	v_min_f32_e64 v46, -v46, s60
	v_min_f32_e64 v47, -v47, s60
	v_exp_f32_e32 v46, v46
	v_exp_f32_e32 v47, v47
	v_mul_f32_e32 v42, v42, v34
	v_cmp_lt_i32_e32 vcc, 19, v134
	v_mul_f32_e32 v34, v135, v34
	v_add_f32_e32 v130, 1.0, v46
	v_cndmask_b32_e32 v147, 0, v34, vcc
	v_mul_f32_e32 v34, v37, v44
	v_add_f32_e32 v37, 1.0, v45
	v_rcp_f32_e32 v37, v37
	v_add_f32_e32 v132, 1.0, v47
	v_rcp_f32_e32 v130, v130
	v_rcp_f32_e32 v132, v132
	v_cndmask_b32_e32 v42, 1.0, v42, vcc
	v_cmp_lt_i32_e32 vcc, 24, v134
	v_mul_f32_e32 v44, v135, v44
	v_mul_f32_e32 v45, v45, v37
	v_cndmask_b32_e32 v34, 1.0, v34, vcc
	v_cndmask_b32_e32 v44, 0, v44, vcc
	v_cmp_lt_i32_e32 vcc, 25, v134
	v_mul_f32_e32 v37, v135, v37
	v_mul_f32_e32 v46, v46, v130
	v_cndmask_b32_e32 v45, 1.0, v45, vcc
	v_cndmask_b32_e32 v37, 0, v37, vcc
	v_cmp_lt_i32_e32 vcc, 26, v134
	v_mul_f32_e32 v47, v47, v132
	v_cndmask_b32_e64 v47, 1.0, v47, s[0:1]
	v_cndmask_b32_e32 v46, 1.0, v46, vcc
	v_mul_f32_e32 v34, v34, v45
	v_mul_f32_e32 v134, v46, v47
	v_mul_f32_e32 v134, v34, v134
	v_mov_b32_e32 v148, v134
	v_mov_b32_e32 v240, v134
	s_nop 1
	v_permlane32_swap_b32_e32 v148, v240
	v_cndmask_b32_e64 v148, v148, v240, s[2:3]
	v_mul_f32_e32 v34, v135, v130
	v_cndmask_b32_e32 v149, 0, v34, vcc
	v_mul_f32_e32 v34, v135, v132
	v_cndmask_b32_e64 v34, 0, v34, s[0:1]
	s_waitcnt lgkmcnt(0)
	v_cndmask_b32_e64 v130, 1.0, v148, s[2:3]
	v_mul_f32_e32 v135, v34, v130
	v_mul_f32_e32 v34, v36, v145
	v_mul_f32_e32 v36, v43, v42
	v_mul_f32_e32 v36, v34, v36
	v_mul_f32_e32 v32, v32, v38
	v_mul_f32_e32 v34, v142, v39
	v_mov_b32_e32 v150, v36
	v_mov_b32_e32 v240, v36
	s_nop 1
	v_permlane32_swap_b32_e32 v150, v240
	v_cndmask_b32_e64 v150, v150, v240, s[2:3]
	v_mul_f32_e32 v34, v32, v34
	v_mul_f32_e32 v47, v47, v130
	v_mov_b32_e32 v130, v34
	v_mov_b32_e32 v240, v34
	s_nop 1
	v_permlane32_swap_b32_e32 v130, v240
	v_cndmask_b32_e64 v130, v130, v240, s[2:3]
	v_mul_f32_e32 v46, v46, v47
	v_mul_f32_e32 v32, v134, v148
	s_waitcnt lgkmcnt(1)
	v_mul_f32_e32 v132, v36, v150
	v_mul_f32_e32 v45, v45, v46
	v_mul_f32_e32 v46, v37, v46
	s_waitcnt lgkmcnt(0)
	v_cndmask_b32_e64 v134, 1.0, v130, s[2:3]
	v_pk_mul_f32 v[36:37], v[32:33], v[132:133]
	v_pk_mul_f32 v[34:35], v[34:35], v[130:131]
	v_mul_f32_e32 v132, v36, v134
	v_mul_f32_e32 v134, v39, v132
	v_mul_f32_e32 v142, v142, v134
	v_mul_f32_e32 v148, v38, v142
	v_pk_mul_f32 v[38:39], v[34:35], v[36:37]
	v_mov_b32_e32 v130, v39
	v_mov_b32_e32 v240, v39
	s_nop 1
	v_permlane32_swap_b32_e32 v130, v240
	v_cndmask_b32_e64 v130, v130, v240, s[2:3]
	v_mul_f32_e32 v37, v40, v132
	v_mul_f32_e32 v40, v143, v134
	v_mul_f32_e32 v36, v141, v142
	v_mul_f32_e32 v132, v140, v148
	s_waitcnt lgkmcnt(0)
	v_cndmask_b32_e64 v34, 1.0, v130, s[2:3]
	v_mul_f32_e32 v34, v38, v34
	v_mul_f32_e32 v35, v133, v34
	v_mul_f32_e32 v33, v33, v35
	v_mul_f32_e32 v131, v131, v33
	v_mul_f32_e32 v133, v136, v34
	v_mul_f32_e32 v35, v139, v35
	v_mul_f32_e32 v33, v137, v33
	v_mul_f32_e32 v34, v138, v131
	v_cvt_pk_bf16_f32 v34, v34, v33
	v_cvt_pk_bf16_f32 v35, v35, v133
	v_cvt_pk_bf16_f32 v36, v132, v36
	v_cvt_pk_bf16_f32 v37, v40, v37
	v_cndmask_b32_e64 v33, 1.0, v150, s[2:3]
	v_mul_f32_e32 v32, v32, v33
	v_mfma_f32_32x32x16_bf16 v[0:15], v[92:95], v[34:37], v[0:15]
	v_mul_f32_e32 v33, v42, v32
	v_mul_f32_e32 v42, v43, v33
	v_mul_f32_e32 v43, v145, v42
	v_mul_f32_e32 v47, v149, v47
	v_mul_f32_e32 v40, v44, v45
	v_mul_f32_e32 v44, v147, v32
	v_mul_f32_e32 v33, v146, v33
	v_mfma_f32_32x32x16_bf16 v[16:31], v[88:91], v[34:37], v[16:31]
	v_mul_f32_e32 v32, v41, v42
	v_mul_f32_e32 v34, v144, v43
	v_cvt_pk_bf16_f32 v32, v34, v32
	v_cvt_pk_bf16_f32 v33, v33, v44
	v_cvt_pk_bf16_f32 v34, v40, v46
	v_cvt_pk_bf16_f32 v35, v47, v135
	v_mul_f32_e32 v36, v39, v130
	v_mul_f32_e32 v36, v38, v36
	v_mfma_f32_32x32x16_bf16 v[0:15], v[84:87], v[32:35], v[0:15]
	v_log_f32_e32 v36, v36
	s_nop 0
	v_add_f32_e32 v126, v126, v36
	v_mfma_f32_32x32x16_bf16 v[16:31], v[80:83], v[32:35], v[16:31]
	s_branch .LBB0_367
.Lsbq_nomask_2:
	ds_read_b128 v[32:35], v129 offset:9216
	ds_read_b128 v[214:217], v129 offset:9248
	ds_read_b128 v[210:213], v129 offset:9280
	ds_read_b128 v[130:133], v129 offset:9312
	ds_read_b64_tr_b16 v[92:93], v128 offset:49152
	ds_read_b64_tr_b16 v[94:95], v128 offset:50688
	ds_read_b64_tr_b16 v[90:91], v128 offset:50752
	ds_read_b64_tr_b16 v[88:89], v128 offset:49216
	ds_read_b64_tr_b16 v[84:85], v128 offset:52224
	ds_read_b64_tr_b16 v[86:87], v128 offset:53760
	ds_read_b64_tr_b16 v[82:83], v128 offset:53824
	ds_read_b64_tr_b16 v[80:81], v128 offset:52288
	v_exp_f32_e32 v135, v126
	s_waitcnt lgkmcnt(11)
	v_mfma_f32_32x32x16_bf16 v[32:47], v[32:35], v[48:51], 0
	s_waitcnt lgkmcnt(10)
	v_mfma_f32_32x32x16_bf16 v[32:47], v[214:217], v[52:55], v[32:47]
	s_waitcnt lgkmcnt(9)
	v_mfma_f32_32x32x16_bf16 v[32:47], v[210:213], v[56:59], v[32:47]
	s_waitcnt lgkmcnt(8)
	v_mfma_f32_32x32x16_bf16 v[32:47], v[130:133], v[60:63], v[32:47]
	s_nop 11
	v_min_f32_e64 v32, -v32, s60
	v_min_f32_e64 v33, -v33, s60
	v_exp_f32_e32 v32, v32
	v_min_f32_e64 v34, -v34, s60
	v_exp_f32_e32 v33, v33
	v_exp_f32_e32 v34, v34
	v_min_f32_e64 v35, -v35, s60
	v_exp_f32_e32 v130, v35
	v_add_f32_e32 v35, 1.0, v32
	v_add_f32_e32 v131, 1.0, v33
	v_rcp_f32_e32 v35, v35
	v_add_f32_e32 v132, 1.0, v34
	v_rcp_f32_e32 v131, v131
	v_min_f32_e64 v36, -v36, s60
	v_rcp_f32_e32 v132, v132
	v_exp_f32_e32 v36, v36
	v_add_f32_e32 v133, 1.0, v130
	v_rcp_f32_e32 v136, v133
	v_mul_f32_e32 v32, v32, v35
	v_mul_f32_e32 v138, v135, v35
	v_mul_f32_e32 v33, v33, v131
	v_mul_f32_e32 v137, v135, v131
	v_mov_b32_e32 v35, v32
	v_mul_f32_e32 v34, v34, v132
	v_mul_f32_e32 v139, v135, v132
	v_mov_b32_e32 v131, v33
	v_min_f32_e64 v39, -v39, s60
	v_mov_b32_e32 v33, v34
	v_add_f32_e32 v34, 1.0, v36
	v_rcp_f32_e32 v34, v34
	v_mul_f32_e32 v133, v130, v136
	v_exp_f32_e32 v39, v39
	v_mul_f32_e32 v136, v135, v136
	v_mul_f32_e32 v32, v36, v34
	v_min_f32_e64 v36, -v37, s60
	v_exp_f32_e32 v36, v36
	v_mul_f32_e32 v140, v135, v34
	v_add_f32_e32 v34, 1.0, v36
	v_rcp_f32_e32 v34, v34
	v_min_f32_e64 v37, -v38, s60
	v_exp_f32_e32 v37, v37
	v_mul_f32_e32 v38, v36, v34
	v_mul_f32_e32 v141, v135, v34
	v_min_f32_e64 v42, -v42, s60
	v_add_f32_e32 v36, 1.0, v37
	v_rcp_f32_e32 v36, v36
	v_exp_f32_e32 v42, v42
	v_mul_f32_e32 v142, v37, v36
	v_add_f32_e32 v37, 1.0, v39
	v_rcp_f32_e32 v37, v37
	v_mul_f32_e32 v143, v135, v36
	v_mul_f32_e32 v39, v39, v37
	v_min_f32_e64 v36, -v40, s60
	v_exp_f32_e32 v36, v36
	v_mul_f32_e32 v40, v135, v37
	v_min_f32_e64 v37, -v41, s60
	v_exp_f32_e32 v37, v37
	v_add_f32_e32 v34, 1.0, v36
	v_rcp_f32_e32 v34, v34
	v_add_f32_e32 v41, 1.0, v37
	v_rcp_f32_e32 v41, v41
	v_mul_f32_e32 v36, v36, v34
	v_mul_f32_e32 v144, v135, v34
	v_mul_f32_e32 v145, v37, v41
	v_add_f32_e32 v37, 1.0, v42
	v_rcp_f32_e32 v37, v37
	v_min_f32_e64 v45, -v45, s60
	v_mul_f32_e32 v41, v135, v41
	v_mul_f32_e32 v34, v42, v37
	v_min_f32_e64 v42, -v43, s60
	v_exp_f32_e32 v42, v42
	v_mov_b32_e32 v43, v34
	v_mul_f32_e32 v146, v135, v37
	v_min_f32_e64 v37, -v44, s60
	v_exp_f32_e32 v37, v37
	v_add_f32_e32 v34, 1.0, v42
	v_rcp_f32_e32 v34, v34
	v_add_f32_e32 v44, 1.0, v37
	v_rcp_f32_e32 v44, v44
	v_exp_f32_e32 v45, v45
	v_min_f32_e64 v46, -v46, s60
	v_min_f32_e64 v47, -v47, s60
	v_exp_f32_e32 v46, v46
	v_exp_f32_e32 v47, v47
	v_mul_f32_e32 v42, v42, v34
	v_mul_f32_e32 v147, v135, v34
	v_add_f32_e32 v130, 1.0, v46
	v_mul_f32_e32 v34, v37, v44
	v_add_f32_e32 v37, 1.0, v45
	v_rcp_f32_e32 v37, v37
	v_add_f32_e32 v132, 1.0, v47
	v_rcp_f32_e32 v130, v130
	v_rcp_f32_e32 v132, v132
	v_mul_f32_e32 v44, v135, v44
	v_mul_f32_e32 v45, v45, v37
	v_mul_f32_e32 v37, v135, v37
	v_mul_f32_e32 v46, v46, v130
	v_mul_f32_e32 v47, v47, v132
	v_mul_f32_e32 v34, v34, v45
	v_mul_f32_e32 v134, v46, v47
	v_mul_f32_e32 v134, v34, v134
	v_mov_b32_e32 v148, v134
	v_mov_b32_e32 v240, v134
	s_nop 1
	v_permlane32_swap_b32_e32 v148, v240
	v_cndmask_b32_e64 v148, v148, v240, s[2:3]
	v_mul_f32_e32 v149, v135, v130
	v_mul_f32_e32 v34, v135, v132
	s_waitcnt lgkmcnt(0)
	v_cndmask_b32_e64 v130, 1.0, v148, s[2:3]
	v_mul_f32_e32 v135, v34, v130
	v_mul_f32_e32 v34, v36, v145
	v_mul_f32_e32 v36, v43, v42
	v_mul_f32_e32 v36, v34, v36
	v_mul_f32_e32 v32, v32, v38
	v_mul_f32_e32 v34, v142, v39
	v_mov_b32_e32 v150, v36
	v_mov_b32_e32 v240, v36
	s_nop 1
	v_permlane32_swap_b32_e32 v150, v240
	v_cndmask_b32_e64 v150, v150, v240, s[2:3]
	v_mul_f32_e32 v34, v32, v34
	v_mul_f32_e32 v47, v47, v130
	v_mov_b32_e32 v130, v34
	v_mov_b32_e32 v240, v34
	s_nop 1
	v_permlane32_swap_b32_e32 v130, v240
	v_cndmask_b32_e64 v130, v130, v240, s[2:3]
	v_mul_f32_e32 v46, v46, v47
	v_mul_f32_e32 v32, v134, v148
	s_waitcnt lgkmcnt(1)
	v_mul_f32_e32 v132, v36, v150
	v_mul_f32_e32 v45, v45, v46
	v_mul_f32_e32 v46, v37, v46
	s_waitcnt lgkmcnt(0)
	v_cndmask_b32_e64 v134, 1.0, v130, s[2:3]
	v_pk_mul_f32 v[36:37], v[32:33], v[132:133]
	v_pk_mul_f32 v[34:35], v[34:35], v[130:131]
	v_mul_f32_e32 v132, v36, v134
	v_mul_f32_e32 v134, v39, v132
	v_mul_f32_e32 v142, v142, v134
	v_mul_f32_e32 v148, v38, v142
	v_pk_mul_f32 v[38:39], v[34:35], v[36:37]
	v_mov_b32_e32 v130, v39
	v_mov_b32_e32 v240, v39
	s_nop 1
	v_permlane32_swap_b32_e32 v130, v240
	v_cndmask_b32_e64 v130, v130, v240, s[2:3]
	v_mul_f32_e32 v37, v40, v132
	v_mul_f32_e32 v40, v143, v134
	v_mul_f32_e32 v36, v141, v142
	v_mul_f32_e32 v132, v140, v148
	s_waitcnt lgkmcnt(0)
	v_cndmask_b32_e64 v34, 1.0, v130, s[2:3]
	v_mul_f32_e32 v34, v38, v34
	v_mul_f32_e32 v35, v133, v34
	v_mul_f32_e32 v33, v33, v35
	v_mul_f32_e32 v131, v131, v33
	v_mul_f32_e32 v133, v136, v34
	v_mul_f32_e32 v35, v139, v35
	v_mul_f32_e32 v33, v137, v33
	v_mul_f32_e32 v34, v138, v131
	v_cvt_pk_bf16_f32 v34, v34, v33
	v_cvt_pk_bf16_f32 v35, v35, v133
	v_cvt_pk_bf16_f32 v36, v132, v36
	v_cvt_pk_bf16_f32 v37, v40, v37
	v_cndmask_b32_e64 v33, 1.0, v150, s[2:3]
	v_mul_f32_e32 v32, v32, v33
	v_mfma_f32_32x32x16_bf16 v[0:15], v[92:95], v[34:37], v[0:15]
	v_mul_f32_e32 v33, v42, v32
	v_mul_f32_e32 v42, v43, v33
	v_mul_f32_e32 v43, v145, v42
	v_mul_f32_e32 v47, v149, v47
	v_mul_f32_e32 v40, v44, v45
	v_mul_f32_e32 v44, v147, v32
	v_mul_f32_e32 v33, v146, v33
	v_mfma_f32_32x32x16_bf16 v[16:31], v[88:91], v[34:37], v[16:31]
	v_mul_f32_e32 v32, v41, v42
	v_mul_f32_e32 v34, v144, v43
	v_cvt_pk_bf16_f32 v32, v34, v32
	v_cvt_pk_bf16_f32 v33, v33, v44
	v_cvt_pk_bf16_f32 v34, v40, v46
	v_cvt_pk_bf16_f32 v35, v47, v135
	v_mul_f32_e32 v36, v39, v130
	v_mul_f32_e32 v36, v38, v36
	v_mfma_f32_32x32x16_bf16 v[0:15], v[84:87], v[32:35], v[0:15]
	v_log_f32_e32 v36, v36
	s_nop 0
	v_add_f32_e32 v126, v126, v36
	v_mfma_f32_32x32x16_bf16 v[16:31], v[80:83], v[32:35], v[16:31]
; __device__ __forceinline__ void sb_unit(const Frame& F, int b, int hd, int qi, int dry) {
;     ...
;             float run = C;
;             if (!meta && key0 + 96 < tqw + 31) SB_HALF(96);
;             if (!meta && key0 + 64 < tqw + 31 && __any(run >= SB_DEAD)) SB_HALF(64);
;             if (!meta && key0 + 32 < tqw + 31 && __any(run >= SB_DEAD)) SB_HALF(32);
.LBB0_367:
	s_or_b32 s0, s34, 1
	s_cmp_ge_i32 s0, s25
	s_cselect_b64 s[0:1], -1, 0
	s_or_b64 s[0:1], s[18:19], s[0:1]
	s_and_b64 vcc, exec, s[0:1]
	s_cbranch_vccnz .LBB0_370
	v_cmp_le_f32_e32 vcc, s22, v126
	s_cbranch_vccz .LBB0_370
	s_add_i32 s61, s34, 64
	s_cmp_le_i32 s61, s25
	s_cbranch_scc1 .Lsbq_nomask_1
	ds_read_b128 v[32:35], v129 offset:4608
	ds_read_b128 v[214:217], v129 offset:4640
	ds_read_b128 v[210:213], v129 offset:4672
	ds_read_b128 v[130:133], v129 offset:4704
	ds_read_b64_tr_b16 v[92:93], v128 offset:43008
	ds_read_b64_tr_b16 v[94:95], v128 offset:44544
	ds_read_b64_tr_b16 v[90:91], v128 offset:44608
	ds_read_b64_tr_b16 v[88:89], v128 offset:43072
	ds_read_b64_tr_b16 v[84:85], v128 offset:46080
	ds_read_b64_tr_b16 v[86:87], v128 offset:47616
	ds_read_b64_tr_b16 v[82:83], v128 offset:47680
	ds_read_b64_tr_b16 v[80:81], v128 offset:46144
	v_exp_f32_e32 v135, v126
	v_sub_u32_e32 v134, v125, v127
	v_cmp_lt_i32_e32 vcc, 0, v134
	s_waitcnt lgkmcnt(11)
	v_mfma_f32_32x32x16_bf16 v[32:47], v[32:35], v[48:51], 0
	v_cmp_lt_i32_e64 s[0:1], 27, v134
	s_waitcnt lgkmcnt(10)
	v_mfma_f32_32x32x16_bf16 v[32:47], v[214:217], v[52:55], v[32:47]
	s_waitcnt lgkmcnt(9)
	v_mfma_f32_32x32x16_bf16 v[32:47], v[210:213], v[56:59], v[32:47]
	s_waitcnt lgkmcnt(8)
	v_mfma_f32_32x32x16_bf16 v[32:47], v[130:133], v[60:63], v[32:47]
	s_nop 11
	v_min_f32_e64 v32, -v32, s60
	v_min_f32_e64 v33, -v33, s60
	v_exp_f32_e32 v32, v32
	v_min_f32_e64 v34, -v34, s60
	v_exp_f32_e32 v33, v33
	v_exp_f32_e32 v34, v34
	v_min_f32_e64 v35, -v35, s60
	v_exp_f32_e32 v130, v35
	v_add_f32_e32 v35, 1.0, v32
	v_add_f32_e32 v131, 1.0, v33
	v_rcp_f32_e32 v35, v35
	v_add_f32_e32 v132, 1.0, v34
	v_rcp_f32_e32 v131, v131
	v_min_f32_e64 v36, -v36, s60
	v_rcp_f32_e32 v132, v132
	v_exp_f32_e32 v36, v36
	v_add_f32_e32 v133, 1.0, v130
	v_rcp_f32_e32 v136, v133
	v_mul_f32_e32 v32, v32, v35
	v_mul_f32_e32 v133, v135, v35
	v_mul_f32_e32 v33, v33, v131
	v_mul_f32_e32 v137, v135, v131
	v_cndmask_b32_e32 v35, 1.0, v32, vcc
	v_cndmask_b32_e32 v138, 0, v133, vcc
	v_cmp_lt_i32_e32 vcc, 1, v134
	v_mul_f32_e32 v34, v34, v132
	v_mul_f32_e32 v32, v135, v132
	v_cndmask_b32_e32 v131, 1.0, v33, vcc
	v_cndmask_b32_e32 v137, 0, v137, vcc
	v_cmp_lt_i32_e32 vcc, 2, v134
	v_min_f32_e64 v39, -v39, s60
	v_cndmask_b32_e32 v33, 1.0, v34, vcc
	v_add_f32_e32 v34, 1.0, v36
	v_rcp_f32_e32 v34, v34
	v_cndmask_b32_e32 v139, 0, v32, vcc
	v_mul_f32_e32 v32, v130, v136
	v_cmp_lt_i32_e32 vcc, 3, v134
	v_exp_f32_e32 v39, v39
	v_cndmask_b32_e32 v133, 1.0, v32, vcc
	v_mul_f32_e32 v32, v135, v136
	v_cndmask_b32_e32 v136, 0, v32, vcc
	v_mul_f32_e32 v32, v36, v34
	v_min_f32_e64 v36, -v37, s60
	v_exp_f32_e32 v36, v36
	v_cmp_lt_i32_e32 vcc, 8, v134
	v_mul_f32_e32 v34, v135, v34
	v_cndmask_b32_e32 v140, 0, v34, vcc
	v_add_f32_e32 v34, 1.0, v36
	v_rcp_f32_e32 v34, v34
	v_min_f32_e64 v37, -v38, s60
	v_exp_f32_e32 v37, v37
	v_cndmask_b32_e32 v32, 1.0, v32, vcc
	v_mul_f32_e32 v36, v36, v34
	v_cmp_lt_i32_e32 vcc, 9, v134
	v_mul_f32_e32 v34, v135, v34
	v_min_f32_e64 v42, -v42, s60
	v_cndmask_b32_e32 v38, 1.0, v36, vcc
	v_add_f32_e32 v36, 1.0, v37
	v_rcp_f32_e32 v36, v36
	v_cndmask_b32_e32 v141, 0, v34, vcc
	v_cmp_lt_i32_e32 vcc, 10, v134
	v_exp_f32_e32 v42, v42
	v_mul_f32_e32 v34, v37, v36
	v_add_f32_e32 v37, 1.0, v39
	v_rcp_f32_e32 v37, v37
	v_cndmask_b32_e32 v142, 1.0, v34, vcc
	v_mul_f32_e32 v34, v135, v36
	v_cndmask_b32_e32 v143, 0, v34, vcc
	v_mul_f32_e32 v34, v39, v37
	v_cmp_lt_i32_e32 vcc, 11, v134
	v_min_f32_e64 v36, -v40, s60
	v_exp_f32_e32 v36, v36
	v_cndmask_b32_e32 v39, 1.0, v34, vcc
	v_mul_f32_e32 v34, v135, v37
	v_min_f32_e64 v37, -v41, s60
	v_exp_f32_e32 v37, v37
	v_cndmask_b32_e32 v40, 0, v34, vcc
	v_add_f32_e32 v34, 1.0, v36
	v_rcp_f32_e32 v34, v34
	v_add_f32_e32 v41, 1.0, v37
	v_rcp_f32_e32 v41, v41
	v_cmp_lt_i32_e32 vcc, 16, v134
	v_mul_f32_e32 v36, v36, v34
	v_mul_f32_e32 v34, v135, v34
	v_cndmask_b32_e32 v144, 0, v34, vcc
	v_mul_f32_e32 v34, v37, v41
	v_add_f32_e32 v37, 1.0, v42
	v_rcp_f32_e32 v37, v37
	v_cndmask_b32_e32 v36, 1.0, v36, vcc
	v_cmp_lt_i32_e32 vcc, 17, v134
	v_min_f32_e64 v45, -v45, s60
	v_cndmask_b32_e32 v145, 1.0, v34, vcc
	v_mul_f32_e32 v34, v135, v41
	v_cndmask_b32_e32 v41, 0, v34, vcc
	v_mul_f32_e32 v34, v42, v37
	v_cmp_lt_i32_e32 vcc, 18, v134
	v_min_f32_e64 v42, -v43, s60
	v_exp_f32_e32 v42, v42
	v_cndmask_b32_e32 v43, 1.0, v34, vcc
	v_mul_f32_e32 v34, v135, v37
	v_min_f32_e64 v37, -v44, s60
	v_exp_f32_e32 v37, v37
	v_cndmask_b32_e32 v146, 0, v34, vcc
	v_add_f32_e32 v34, 1.0, v42
	v_rcp_f32_e32 v34, v34
	v_add_f32_e32 v44, 1.0, v37
	v_rcp_f32_e32 v44, v44
	v_exp_f32_e32 v45, v45
	v_min_f32_e64 v46, -v46, s60
	v_min_f32_e64 v47, -v47, s60
	v_exp_f32_e32 v46, v46
	v_exp_f32_e32 v47, v47
	v_mul_f32_e32 v42, v42, v34
	v_cmp_lt_i32_e32 vcc, 19, v134
	v_mul_f32_e32 v34, v135, v34
	v_add_f32_e32 v130, 1.0, v46
	v_cndmask_b32_e32 v147, 0, v34, vcc
	v_mul_f32_e32 v34, v37, v44
	v_add_f32_e32 v37, 1.0, v45
	v_rcp_f32_e32 v37, v37
	v_add_f32_e32 v132, 1.0, v47
	v_rcp_f32_e32 v130, v130
	v_rcp_f32_e32 v132, v132
	v_cndmask_b32_e32 v42, 1.0, v42, vcc
	v_cmp_lt_i32_e32 vcc, 24, v134
	v_mul_f32_e32 v44, v135, v44
	v_mul_f32_e32 v45, v45, v37
	v_cndmask_b32_e32 v34, 1.0, v34, vcc
	v_cndmask_b32_e32 v44, 0, v44, vcc
	v_cmp_lt_i32_e32 vcc, 25, v134
	v_mul_f32_e32 v37, v135, v37
	v_mul_f32_e32 v46, v46, v130
	v_cndmask_b32_e32 v45, 1.0, v45, vcc
	v_cndmask_b32_e32 v37, 0, v37, vcc
	v_cmp_lt_i32_e32 vcc, 26, v134
	v_mul_f32_e32 v47, v47, v132
	v_cndmask_b32_e64 v47, 1.0, v47, s[0:1]
	v_cndmask_b32_e32 v46, 1.0, v46, vcc
	v_mul_f32_e32 v34, v34, v45
	v_mul_f32_e32 v134, v46, v47
	v_mul_f32_e32 v134, v34, v134
	v_mov_b32_e32 v148, v134
	v_mov_b32_e32 v240, v134
	s_nop 1
	v_permlane32_swap_b32_e32 v148, v240
	v_cndmask_b32_e64 v148, v148, v240, s[2:3]
	v_mul_f32_e32 v34, v135, v130
	v_cndmask_b32_e32 v149, 0, v34, vcc
	v_mul_f32_e32 v34, v135, v132
	v_cndmask_b32_e64 v34, 0, v34, s[0:1]
	s_waitcnt lgkmcnt(0)
	v_cndmask_b32_e64 v130, 1.0, v148, s[2:3]
	v_mul_f32_e32 v135, v34, v130
	v_mul_f32_e32 v34, v36, v145
	v_mul_f32_e32 v36, v43, v42
	v_mul_f32_e32 v36, v34, v36
	v_mul_f32_e32 v32, v32, v38
	v_mul_f32_e32 v34, v142, v39
	v_mov_b32_e32 v150, v36
	v_mov_b32_e32 v240, v36
	s_nop 1
	v_permlane32_swap_b32_e32 v150, v240
	v_cndmask_b32_e64 v150, v150, v240, s[2:3]
	v_mul_f32_e32 v34, v32, v34
	v_mul_f32_e32 v47, v47, v130
	v_mov_b32_e32 v130, v34
	v_mov_b32_e32 v240, v34
	s_nop 1
	v_permlane32_swap_b32_e32 v130, v240
	v_cndmask_b32_e64 v130, v130, v240, s[2:3]
	v_mul_f32_e32 v46, v46, v47
	v_mul_f32_e32 v32, v134, v148
	s_waitcnt lgkmcnt(1)
	v_mul_f32_e32 v132, v36, v150
	v_mul_f32_e32 v45, v45, v46
	v_mul_f32_e32 v46, v37, v46
	s_waitcnt lgkmcnt(0)
	v_cndmask_b32_e64 v134, 1.0, v130, s[2:3]
	v_pk_mul_f32 v[36:37], v[32:33], v[132:133]
	v_pk_mul_f32 v[34:35], v[34:35], v[130:131]
	v_mul_f32_e32 v132, v36, v134
	v_mul_f32_e32 v134, v39, v132
	v_mul_f32_e32 v142, v142, v134
	v_mul_f32_e32 v148, v38, v142
	v_pk_mul_f32 v[38:39], v[34:35], v[36:37]
	v_mov_b32_e32 v130, v39
	v_mov_b32_e32 v240, v39
	s_nop 1
	v_permlane32_swap_b32_e32 v130, v240
	v_cndmask_b32_e64 v130, v130, v240, s[2:3]
	v_mul_f32_e32 v37, v40, v132
	v_mul_f32_e32 v40, v143, v134
	v_mul_f32_e32 v36, v141, v142
	v_mul_f32_e32 v132, v140, v148
	s_waitcnt lgkmcnt(0)
	v_cndmask_b32_e64 v34, 1.0, v130, s[2:3]
	v_mul_f32_e32 v34, v38, v34
	v_mul_f32_e32 v35, v133, v34
	v_mul_f32_e32 v33, v33, v35
	v_mul_f32_e32 v131, v131, v33
	v_mul_f32_e32 v133, v136, v34
	v_mul_f32_e32 v35, v139, v35
	v_mul_f32_e32 v33, v137, v33
	v_mul_f32_e32 v34, v138, v131
	v_cvt_pk_bf16_f32 v34, v34, v33
	v_cvt_pk_bf16_f32 v35, v35, v133
	v_cvt_pk_bf16_f32 v36, v132, v36
	v_cvt_pk_bf16_f32 v37, v40, v37
	v_cndmask_b32_e64 v33, 1.0, v150, s[2:3]
	v_mul_f32_e32 v32, v32, v33
	v_mfma_f32_32x32x16_bf16 v[0:15], v[92:95], v[34:37], v[0:15]
	v_mul_f32_e32 v33, v42, v32
	v_mul_f32_e32 v42, v43, v33
	v_mul_f32_e32 v43, v145, v42
	v_mul_f32_e32 v47, v149, v47
	v_mul_f32_e32 v40, v44, v45
	v_mul_f32_e32 v44, v147, v32
	v_mul_f32_e32 v33, v146, v33
	v_mfma_f32_32x32x16_bf16 v[16:31], v[88:91], v[34:37], v[16:31]
	v_mul_f32_e32 v32, v41, v42
	v_mul_f32_e32 v34, v144, v43
	v_cvt_pk_bf16_f32 v32, v34, v32
	v_cvt_pk_bf16_f32 v33, v33, v44
	v_cvt_pk_bf16_f32 v34, v40, v46
	v_cvt_pk_bf16_f32 v35, v47, v135
	v_mul_f32_e32 v36, v39, v130
	v_mul_f32_e32 v36, v38, v36
	v_mfma_f32_32x32x16_bf16 v[0:15], v[84:87], v[32:35], v[0:15]
	v_log_f32_e32 v36, v36
	s_nop 0
	v_add_f32_e32 v126, v126, v36
	v_mfma_f32_32x32x16_bf16 v[16:31], v[80:83], v[32:35], v[16:31]
	s_branch .LBB0_370
.Lsbq_nomask_1:
	ds_read_b128 v[32:35], v129 offset:4608
	ds_read_b128 v[214:217], v129 offset:4640
	ds_read_b128 v[210:213], v129 offset:4672
	ds_read_b128 v[130:133], v129 offset:4704
	ds_read_b64_tr_b16 v[92:93], v128 offset:43008
	ds_read_b64_tr_b16 v[94:95], v128 offset:44544
	ds_read_b64_tr_b16 v[90:91], v128 offset:44608
	ds_read_b64_tr_b16 v[88:89], v128 offset:43072
	ds_read_b64_tr_b16 v[84:85], v128 offset:46080
	ds_read_b64_tr_b16 v[86:87], v128 offset:47616
	ds_read_b64_tr_b16 v[82:83], v128 offset:47680
	ds_read_b64_tr_b16 v[80:81], v128 offset:46144
	v_exp_f32_e32 v135, v126
	s_waitcnt lgkmcnt(11)
	v_mfma_f32_32x32x16_bf16 v[32:47], v[32:35], v[48:51], 0
	s_waitcnt lgkmcnt(10)
	v_mfma_f32_32x32x16_bf16 v[32:47], v[214:217], v[52:55], v[32:47]
	s_waitcnt lgkmcnt(9)
	v_mfma_f32_32x32x16_bf16 v[32:47], v[210:213], v[56:59], v[32:47]
	s_waitcnt lgkmcnt(8)
	v_mfma_f32_32x32x16_bf16 v[32:47], v[130:133], v[60:63], v[32:47]
	s_nop 11
	v_min_f32_e64 v32, -v32, s60
	v_min_f32_e64 v33, -v33, s60
	v_exp_f32_e32 v32, v32
	v_min_f32_e64 v34, -v34, s60
	v_exp_f32_e32 v33, v33
	v_exp_f32_e32 v34, v34
	v_min_f32_e64 v35, -v35, s60
	v_exp_f32_e32 v130, v35
	v_add_f32_e32 v35, 1.0, v32
	v_add_f32_e32 v131, 1.0, v33
	v_rcp_f32_e32 v35, v35
	v_add_f32_e32 v132, 1.0, v34
	v_rcp_f32_e32 v131, v131
	v_min_f32_e64 v36, -v36, s60
	v_rcp_f32_e32 v132, v132
	v_exp_f32_e32 v36, v36
	v_add_f32_e32 v133, 1.0, v130
	v_rcp_f32_e32 v136, v133
	v_mul_f32_e32 v32, v32, v35
	v_mul_f32_e32 v138, v135, v35
	v_mul_f32_e32 v33, v33, v131
	v_mul_f32_e32 v137, v135, v131
	v_mov_b32_e32 v35, v32
	v_mul_f32_e32 v34, v34, v132
	v_mul_f32_e32 v139, v135, v132
	v_mov_b32_e32 v131, v33
	v_min_f32_e64 v39, -v39, s60
	v_mov_b32_e32 v33, v34
	v_add_f32_e32 v34, 1.0, v36
	v_rcp_f32_e32 v34, v34
	v_mul_f32_e32 v133, v130, v136
	v_exp_f32_e32 v39, v39
	v_mul_f32_e32 v136, v135, v136
	v_mul_f32_e32 v32, v36, v34
	v_min_f32_e64 v36, -v37, s60
	v_exp_f32_e32 v36, v36
	v_mul_f32_e32 v140, v135, v34
	v_add_f32_e32 v34, 1.0, v36
	v_rcp_f32_e32 v34, v34
	v_min_f32_e64 v37, -v38, s60
	v_exp_f32_e32 v37, v37
	v_mul_f32_e32 v38, v36, v34
	v_mul_f32_e32 v141, v135, v34
	v_min_f32_e64 v42, -v42, s60
	v_add_f32_e32 v36, 1.0, v37
	v_rcp_f32_e32 v36, v36
	v_exp_f32_e32 v42, v42
	v_mul_f32_e32 v142, v37, v36
	v_add_f32_e32 v37, 1.0, v39
	v_rcp_f32_e32 v37, v37
	v_mul_f32_e32 v143, v135, v36
	v_mul_f32_e32 v39, v39, v37
	v_min_f32_e64 v36, -v40, s60
	v_exp_f32_e32 v36, v36
	v_mul_f32_e32 v40, v135, v37
	v_min_f32_e64 v37, -v41, s60
	v_exp_f32_e32 v37, v37
	v_add_f32_e32 v34, 1.0, v36
	v_rcp_f32_e32 v34, v34
	v_add_f32_e32 v41, 1.0, v37
	v_rcp_f32_e32 v41, v41
	v_mul_f32_e32 v36, v36, v34
	v_mul_f32_e32 v144, v135, v34
	v_mul_f32_e32 v145, v37, v41
	v_add_f32_e32 v37, 1.0, v42
	v_rcp_f32_e32 v37, v37
	v_min_f32_e64 v45, -v45, s60
	v_mul_f32_e32 v41, v135, v41
	v_mul_f32_e32 v34, v42, v37
	v_min_f32_e64 v42, -v43, s60
	v_exp_f32_e32 v42, v42
	v_mov_b32_e32 v43, v34
	v_mul_f32_e32 v146, v135, v37
	v_min_f32_e64 v37, -v44, s60
	v_exp_f32_e32 v37, v37
	v_add_f32_e32 v34, 1.0, v42
	v_rcp_f32_e32 v34, v34
	v_add_f32_e32 v44, 1.0, v37
	v_rcp_f32_e32 v44, v44
	v_exp_f32_e32 v45, v45
	v_min_f32_e64 v46, -v46, s60
	v_min_f32_e64 v47, -v47, s60
	v_exp_f32_e32 v46, v46
	v_exp_f32_e32 v47, v47
	v_mul_f32_e32 v42, v42, v34
	v_mul_f32_e32 v147, v135, v34
	v_add_f32_e32 v130, 1.0, v46
	v_mul_f32_e32 v34, v37, v44
	v_add_f32_e32 v37, 1.0, v45
	v_rcp_f32_e32 v37, v37
	v_add_f32_e32 v132, 1.0, v47
	v_rcp_f32_e32 v130, v130
	v_rcp_f32_e32 v132, v132
	v_mul_f32_e32 v44, v135, v44
	v_mul_f32_e32 v45, v45, v37
	v_mul_f32_e32 v37, v135, v37
	v_mul_f32_e32 v46, v46, v130
	v_mul_f32_e32 v47, v47, v132
	v_mul_f32_e32 v34, v34, v45
	v_mul_f32_e32 v134, v46, v47
	v_mul_f32_e32 v134, v34, v134
	v_mov_b32_e32 v148, v134
	v_mov_b32_e32 v240, v134
	s_nop 1
	v_permlane32_swap_b32_e32 v148, v240
	v_cndmask_b32_e64 v148, v148, v240, s[2:3]
	v_mul_f32_e32 v149, v135, v130
	v_mul_f32_e32 v34, v135, v132
	s_waitcnt lgkmcnt(0)
	v_cndmask_b32_e64 v130, 1.0, v148, s[2:3]
	v_mul_f32_e32 v135, v34, v130
	v_mul_f32_e32 v34, v36, v145
	v_mul_f32_e32 v36, v43, v42
	v_mul_f32_e32 v36, v34, v36
	v_mul_f32_e32 v32, v32, v38
	v_mul_f32_e32 v34, v142, v39
	v_mov_b32_e32 v150, v36
	v_mov_b32_e32 v240, v36
	s_nop 1
	v_permlane32_swap_b32_e32 v150, v240
	v_cndmask_b32_e64 v150, v150, v240, s[2:3]
	v_mul_f32_e32 v34, v32, v34
	v_mul_f32_e32 v47, v47, v130
	v_mov_b32_e32 v130, v34
	v_mov_b32_e32 v240, v34
	s_nop 1
	v_permlane32_swap_b32_e32 v130, v240
	v_cndmask_b32_e64 v130, v130, v240, s[2:3]
	v_mul_f32_e32 v46, v46, v47
	v_mul_f32_e32 v32, v134, v148
	s_waitcnt lgkmcnt(1)
	v_mul_f32_e32 v132, v36, v150
	v_mul_f32_e32 v45, v45, v46
	v_mul_f32_e32 v46, v37, v46
	s_waitcnt lgkmcnt(0)
	v_cndmask_b32_e64 v134, 1.0, v130, s[2:3]
	v_pk_mul_f32 v[36:37], v[32:33], v[132:133]
	v_pk_mul_f32 v[34:35], v[34:35], v[130:131]
	v_mul_f32_e32 v132, v36, v134
	v_mul_f32_e32 v134, v39, v132
	v_mul_f32_e32 v142, v142, v134
	v_mul_f32_e32 v148, v38, v142
	v_pk_mul_f32 v[38:39], v[34:35], v[36:37]
	v_mov_b32_e32 v130, v39
	v_mov_b32_e32 v240, v39
	s_nop 1
	v_permlane32_swap_b32_e32 v130, v240
	v_cndmask_b32_e64 v130, v130, v240, s[2:3]
	v_mul_f32_e32 v37, v40, v132
	v_mul_f32_e32 v40, v143, v134
	v_mul_f32_e32 v36, v141, v142
	v_mul_f32_e32 v132, v140, v148
	s_waitcnt lgkmcnt(0)
	v_cndmask_b32_e64 v34, 1.0, v130, s[2:3]
	v_mul_f32_e32 v34, v38, v34
	v_mul_f32_e32 v35, v133, v34
	v_mul_f32_e32 v33, v33, v35
	v_mul_f32_e32 v131, v131, v33
	v_mul_f32_e32 v133, v136, v34
	v_mul_f32_e32 v35, v139, v35
	v_mul_f32_e32 v33, v137, v33
	v_mul_f32_e32 v34, v138, v131
	v_cvt_pk_bf16_f32 v34, v34, v33
	v_cvt_pk_bf16_f32 v35, v35, v133
	v_cvt_pk_bf16_f32 v36, v132, v36
	v_cvt_pk_bf16_f32 v37, v40, v37
	v_cndmask_b32_e64 v33, 1.0, v150, s[2:3]
	v_mul_f32_e32 v32, v32, v33
	v_mfma_f32_32x32x16_bf16 v[0:15], v[92:95], v[34:37], v[0:15]
	v_mul_f32_e32 v33, v42, v32
	v_mul_f32_e32 v42, v43, v33
	v_mul_f32_e32 v43, v145, v42
	v_mul_f32_e32 v47, v149, v47
	v_mul_f32_e32 v40, v44, v45
	v_mul_f32_e32 v44, v147, v32
	v_mul_f32_e32 v33, v146, v33
	v_mfma_f32_32x32x16_bf16 v[16:31], v[88:91], v[34:37], v[16:31]
	v_mul_f32_e32 v32, v41, v42
	v_mul_f32_e32 v34, v144, v43
	v_cvt_pk_bf16_f32 v32, v34, v32
	v_cvt_pk_bf16_f32 v33, v33, v44
	v_cvt_pk_bf16_f32 v34, v40, v46
	v_cvt_pk_bf16_f32 v35, v47, v135
	v_mul_f32_e32 v36, v39, v130
	v_mul_f32_e32 v36, v38, v36
	v_mfma_f32_32x32x16_bf16 v[0:15], v[84:87], v[32:35], v[0:15]
	v_log_f32_e32 v36, v36
	s_nop 0
	v_add_f32_e32 v126, v126, v36
	v_mfma_f32_32x32x16_bf16 v[16:31], v[80:83], v[32:35], v[16:31]
